# attention: tile loops unrolled 3x (ring stage offsets as ds_read immediates, -6 VALU/tile) + lazy row-max (permlane only in rare rescale path, -3 VALU/tile)
# speedup vs baseline: 1.0083x; 1.0083x over previous
; #define LAS __attribute__((address_space(3)))
; __device__ __forceinline__ float max_xor32(float x) { const u32x2 r = __builtin_amdgcn_permlane32_swap(__float_as_uint(x), __float_as_uint(x), false, false); return fmaxf(__uint_as_float(r.x), __uint_as_float(r.y)); }
; #define MFMA32(a, b, c) __builtin_amdgcn_mfma_f32_32x32x16_bf16((a), (b), (c), 0, 0, 0)
; #define ATT_KRD(dst, g) do { _Pragma("unroll") for (int q_ = 0; q_ < 4; ++q_) dst[q_] = *(const LAS bf16x8*)(kb + kro[q_] + (g) * 128); } while (0)
; __device__ __forceinline__ void attn_unit(LAS unsigned char* lds, const bf16_t* Qg, const bf16_t* Kg, const bf16_t* Vtg, bf16_t* Og, int bh, int qb, int tid_, int wave, int lane_) {
;     ...
;     for (int j = 0; j < nt; ++j) {
;         const int relc = 64 * (j - 2 * qb) + 32 * kh - 32 * rg;
;         const int j3 = (j + 3 < nt) ? j + 3 : nt - 1, j2 = (j + 2 < nt) ? j + 2 : nt - 1;
;         const LAS unsigned char* kb = lds + KRING + s1 * KTILE;
;         const LAS unsigned char* vb = lds + s0 * VTILE;
;         if (relc >= 0) {
;             const int thr = (relc == 0) ? r : -1;
; #pragma unroll
;             for (int i = 0; i < 16; ++i) { const int key = (i & 3) + 8 * (i >> 2) + 4 * hi; if (key > thr) sc[i] = NINF; }
;         }
;     ...
;         bf16x8 fa[4], fb[4];
;         ATT_KRD(fa, 0); ATT_KRD(fb, 1);
; #pragma unroll
;         for (int i = 0; i < 16; ++i) sn[i] = 0.f;
;         float mx = sc[0];
; #pragma unroll
;         for (int i = 1; i < 16; ++i) mx = fmaxf(mx, sc[i]);
;         mx = max_xor32(mx);
; #pragma unroll
;         for (int q = 0; q < 4; ++q) sn = MFMA32(fa[q], qf[q], sn);
;         ATT_KRD(fa, 2);
;         __builtin_amdgcn_sched_barrier(0);
;         if (__builtin_amdgcn_ballot_w64(mx > mrun + 8.f) != 0ull) {
;             const float mnew = fmaxf(mrun, mx); const float alpha = __builtin_amdgcn_exp2f(mrun - mnew); mrun = mnew; lrun *= alpha;
; #pragma unroll
;             for (int dt = 0; dt < 4; ++dt) o[dt] = o[dt] * alpha;
;         }
;         float ps = 0.f; u32x4 p0, p1;
; #pragma unroll
;         for (int q = 0; q < 4; ++q) sn = MFMA32(fb[q], qf[4 + q], sn);
; #pragma unroll
.LBB0_477:
.LBB0_478:
	ds_read_b128 v[64:67], v191 offset:24576
	ds_read_b128 v[144:147], v197 offset:24576
	ds_read_b128 v[206:209], v200 offset:24576
	ds_read_b128 v[164:167], v191 offset:24704
	ds_read_b128 v[152:155], v199 offset:24576
	ds_read_b128 v[168:171], v199 offset:24704
	s_waitcnt lgkmcnt(0)
	v_mfma_f32_32x32x16_bf16 v[64:79], v[64:67], v[96:99], v[226:241]
	v_max_f32_e32 v149, v80, v81
	v_max3_f32 v157, v149, v82, v83
	ds_read_b128 v[148:151], v191 offset:24832
	s_waitcnt lgkmcnt(5)
	v_mfma_f32_32x32x16_bf16 v[64:79], v[144:147], v[100:103], v[64:79]
	v_max3_f32 v144, v157, v84, v85
	v_max3_f32 v144, v144, v86, v87
	v_max3_f32 v144, v144, v88, v89
	v_max3_f32 v144, v144, v90, v91
	v_max3_f32 v144, v144, v92, v93
	v_max3_f32 v193, v144, v94, v95
	s_waitcnt lgkmcnt(2)
	v_mfma_f32_32x32x16_bf16 v[64:79], v[152:155], v[104:107], v[64:79]
	ds_read_b128 v[172:175], v197 offset:24704
	ds_read_b128 v[156:159], v197 offset:24832
	ds_read_b128 v[152:155], v199 offset:24832
	ds_read_b128 v[160:163], v200 offset:24704
	ds_read_b128 v[144:147], v200 offset:24832
	v_mfma_f32_32x32x16_bf16 v[64:79], v[206:209], v[108:111], v[64:79]
	v_cmp_gt_f32_e32 vcc, v193, v242
	s_cbranch_vccz .LBB0_480
	v_mov_b32_e32 v194, v193
	s_nop 1
	v_permlane32_swap_b32_e32 v193, v194
	v_max_f32_e32 v205, v193, v194
	v_add_f32_e32 v192, v205, v243
	v_max_f32_e32 v193, v204, v204
	v_max_f32_e32 v193, v193, v192
	v_sub_f32_e32 v192, v204, v193
	v_sub_f32_e32 v244, v243, v193
	v_exp_f32_e32 v192, v192
	v_mov_b32_e32 v204, v193
	v_mov_b32_e32 v243, v193
	v_mov_b32_e32 v242, 0x41000000
	v_pk_mul_f32 v[62:63], v[62:63], v[192:193] op_sel_hi:[1,0]
	v_pk_mul_f32 v[60:61], v[60:61], v[192:193] op_sel_hi:[1,0]
	v_pk_mul_f32 v[58:59], v[58:59], v[192:193] op_sel_hi:[1,0]
	v_pk_mul_f32 v[56:57], v[56:57], v[192:193] op_sel_hi:[1,0]
	v_pk_mul_f32 v[54:55], v[54:55], v[192:193] op_sel_hi:[1,0]
	v_pk_mul_f32 v[52:53], v[52:53], v[192:193] op_sel_hi:[1,0]
	v_pk_mul_f32 v[50:51], v[50:51], v[192:193] op_sel_hi:[1,0]
	v_pk_mul_f32 v[48:49], v[48:49], v[192:193] op_sel_hi:[1,0]
	v_pk_mul_f32 v[46:47], v[46:47], v[192:193] op_sel_hi:[1,0]
	v_pk_mul_f32 v[44:45], v[44:45], v[192:193] op_sel_hi:[1,0]
	v_pk_mul_f32 v[42:43], v[42:43], v[192:193] op_sel_hi:[1,0]
	v_pk_mul_f32 v[40:41], v[40:41], v[192:193] op_sel_hi:[1,0]
	v_pk_mul_f32 v[38:39], v[38:39], v[192:193] op_sel_hi:[1,0]
	v_pk_mul_f32 v[36:37], v[36:37], v[192:193] op_sel_hi:[1,0]
	v_pk_mul_f32 v[34:35], v[34:35], v[192:193] op_sel_hi:[1,0]
	v_pk_mul_f32 v[32:33], v[32:33], v[192:193] op_sel_hi:[1,0]
	v_pk_mul_f32 v[30:31], v[30:31], v[192:193] op_sel_hi:[1,0]
	v_pk_mul_f32 v[28:29], v[28:29], v[192:193] op_sel_hi:[1,0]
	v_pk_mul_f32 v[26:27], v[26:27], v[192:193] op_sel_hi:[1,0]
	v_pk_mul_f32 v[24:25], v[24:25], v[192:193] op_sel_hi:[1,0]
	v_pk_mul_f32 v[22:23], v[22:23], v[192:193] op_sel_hi:[1,0]
	v_pk_mul_f32 v[20:21], v[20:21], v[192:193] op_sel_hi:[1,0]
	v_pk_mul_f32 v[18:19], v[18:19], v[192:193] op_sel_hi:[1,0]
	v_pk_mul_f32 v[16:17], v[16:17], v[192:193] op_sel_hi:[1,0]
	v_pk_mul_f32 v[14:15], v[14:15], v[192:193] op_sel_hi:[1,0]
	v_pk_mul_f32 v[12:13], v[12:13], v[192:193] op_sel_hi:[1,0]
	v_pk_mul_f32 v[10:11], v[10:11], v[192:193] op_sel_hi:[1,0]
	v_pk_mul_f32 v[8:9], v[8:9], v[192:193] op_sel_hi:[1,0]
	v_pk_mul_f32 v[6:7], v[6:7], v[192:193] op_sel_hi:[1,0]
	v_pk_mul_f32 v[4:5], v[4:5], v[192:193] op_sel_hi:[1,0]
	v_pk_mul_f32 v[2:3], v[2:3], v[192:193] op_sel_hi:[1,0]
	v_pk_mul_f32 v[0:1], v[0:1], v[192:193] op_sel_hi:[1,0]
	v_mul_f32_e32 v190, v190, v192
	v_add_f32_e32 v80, v80, v244
	v_add_f32_e32 v81, v81, v244
	v_add_f32_e32 v82, v82, v244
	v_add_f32_e32 v83, v83, v244
	v_add_f32_e32 v84, v84, v244
	v_add_f32_e32 v85, v85, v244
	v_add_f32_e32 v86, v86, v244
	v_add_f32_e32 v87, v87, v244
	v_add_f32_e32 v88, v88, v244
	v_add_f32_e32 v89, v89, v244
	v_add_f32_e32 v90, v90, v244
	v_add_f32_e32 v91, v91, v244
	v_add_f32_e32 v92, v92, v244
	v_add_f32_e32 v93, v93, v244
	v_add_f32_e32 v94, v94, v244
	v_add_f32_e32 v95, v95, v244
	v_add_f32_e32 v64, v64, v244
	v_add_f32_e32 v65, v65, v244
	v_add_f32_e32 v66, v66, v244
	v_add_f32_e32 v67, v67, v244
	v_add_f32_e32 v68, v68, v244
	v_add_f32_e32 v69, v69, v244
	v_add_f32_e32 v70, v70, v244
	v_add_f32_e32 v71, v71, v244
	v_add_f32_e32 v72, v72, v244
	v_add_f32_e32 v73, v73, v244
	v_add_f32_e32 v74, v74, v244
	v_add_f32_e32 v75, v75, v244
	v_add_f32_e32 v76, v76, v244
	v_add_f32_e32 v77, v77, v244
	v_add_f32_e32 v78, v78, v244
	v_add_f32_e32 v79, v79, v244
	v_sub_f32_e32 v226, 0, v193
	v_mov_b32_e32 v227, v226
	v_mov_b32_e32 v228, v226
	v_mov_b32_e32 v229, v226
	v_mov_b32_e32 v230, v226
	v_mov_b32_e32 v231, v226
	v_mov_b32_e32 v232, v226
	v_mov_b32_e32 v233, v226
	v_mov_b32_e32 v234, v226
	v_mov_b32_e32 v235, v226
	v_mov_b32_e32 v236, v226
	v_mov_b32_e32 v237, v226
	v_mov_b32_e32 v238, v226
	v_mov_b32_e32 v239, v226
	v_mov_b32_e32 v240, v226
	v_mov_b32_e32 v241, v226
; __device__ __forceinline__ unsigned pk2(float a, float b) { f32x2_t v = {a, b}; bf16x2v_t r = __builtin_convertvector(v, bf16x2v_t); return __builtin_bit_cast(unsigned, r); }
; __device__ __forceinline__ void attn_unit(LAS unsigned char* lds, const bf16_t* Qg, const bf16_t* Kg, const bf16_t* Vtg, bf16_t* Og, int bh, int qb, int tid_, int wave, int lane_) {
;     ...
;         float ps = 0.f; u32x4 p0, p1;
; #pragma unroll
;         for (int q = 0; q < 4; ++q) sn = MFMA32(fb[q], qf[4 + q], sn);
; #pragma unroll
;         for (int i = 0; i < 8; ++i) { sc[i] = __builtin_amdgcn_exp2f(sc[i] - mrun); ps += sc[i]; }
;         p0.x = pk2(sc[0], sc[1]); p0.y = pk2(sc[2], sc[3]); p0.z = pk2(sc[4], sc[5]); p0.w = pk2(sc[6], sc[7]);
;         __builtin_amdgcn_sched_barrier(0);
; #pragma unroll
;         for (int dt = 0; dt < 4; ++dt) fb[dt] = *(const LAS bf16x8*)(vb + vro[0] + dt * 4096);
;         __builtin_amdgcn_sched_barrier(0);
;         ATT_ISSUE_K(j3, s0);
;         __builtin_amdgcn_sched_barrier(0);
; #pragma unroll
;         for (int q = 0; q < 4; ++q) sn = MFMA32(fa[q], qf[8 + q], sn);
; #pragma unroll
;         for (int i = 8; i < 12; ++i) { sc[i] = __builtin_amdgcn_exp2f(sc[i] - mrun); ps += sc[i]; }
;         p1.x = pk2(sc[8], sc[9]); p1.y = pk2(sc[10], sc[11]);
;         __builtin_amdgcn_sched_barrier(0);
;         ATT_ISSUE_V(j2, s2);
;         __builtin_amdgcn_sched_barrier(0);
; #pragma unroll
;         for (int dt = 0; dt < 4; ++dt) fa[dt] = *(const LAS bf16x8*)(vb + vro[1] + dt * 4096);
;         { const bf16x8 pf0 = __builtin_bit_cast(bf16x8, p0);
;           o[0] = MFMA32(fb[0], pf0, o[0]); o[1] = MFMA32(fb[1], pf0, o[1]); o[2] = MFMA32(fb[2], pf0, o[2]); o[3] = MFMA32(fb[3], pf0, o[3]); }
; #pragma unroll
;         for (int i = 12; i < 16; ++i) { sc[i] = __builtin_amdgcn_exp2f(sc[i] - mrun); ps += sc[i]; }
;         p1.z = pk2(sc[12], sc[13]); p1.w = pk2(sc[14], sc[15]);
;         lrun += ps;
;         __builtin_amdgcn_sched_barrier(0);
;         { const bf16x8 pf1 = __builtin_bit_cast(bf16x8, p1);
;           o[0] = MFMA32(fa[0], pf1, o[0]); o[1] = MFMA32(fa[1], pf1, o[1]); o[2] = MFMA32(fa[2], pf1, o[2]); o[3] = MFMA32(fa[3], pf1, o[3]); }
;         asm volatile("s_waitcnt vmcnt(5) lgkmcnt(0)" ::: "memory"); __builtin_amdgcn_s_barrier(); asm volatile("" ::: "memory");
;         sc = sn;
;         { const int t = s0; s0 = s1; s1 = s2; s2 = t; }
;     }
.LBB0_480:
	v_mfma_f32_32x32x16_bf16 v[64:79], v[164:167], v[112:115], v[64:79]
	v_exp_f32_e32 v192, v80
	v_exp_f32_e32 v193, v81
	v_exp_f32_e32 v194, v82
	s_waitcnt lgkmcnt(0)
	v_mfma_f32_32x32x16_bf16 v[64:79], v[172:175], v[116:119], v[64:79]
	v_exp_f32_e32 v205, v83
	v_exp_f32_e32 v206, v84
	v_exp_f32_e32 v207, v85
	v_exp_f32_e32 v208, v86
	v_mfma_f32_32x32x16_bf16 v[64:79], v[168:171], v[120:123], v[64:79]
	s_add_i32 s0, s52, 3
	v_exp_f32_e32 v209, v87
	s_cmp_lt_u32 s0, s89
	s_cselect_b32 s0, s0, s45
	s_add_i32 s1, s52, 2
	s_cmp_lt_u32 s52, s44
	s_cselect_b32 s48, s1, s45
	v_cvt_pk_bf16_f32 v246, v192, v193
	v_cvt_pk_bf16_f32 v247, v194, v205
	v_cvt_pk_bf16_f32 v248, v206, v207
	v_cvt_pk_bf16_f32 v249, v208, v209
	ds_read_b128 v[214:217], v225
	ds_read_b128 v[164:167], v225 offset:4096
	ds_read_b128 v[168:171], v225 offset:8192
	ds_read_b128 v[172:175], v225 offset:12288
	v_add_f32_e32 v192, v193, v192
	v_add_f32_e32 v192, v194, v192
	v_add_f32_e32 v192, v205, v192
	v_add_f32_e32 v192, v206, v192
	v_add_f32_e32 v192, v207, v192
	v_add_f32_e32 v192, v208, v192
	v_add_f32_e32 v194, v209, v192
	s_mul_hi_u32 s1, s0, 0x6000
	s_mulk_i32 s0, 0x6000
	s_add_u32 s0, s92, s0
	s_mul_i32 s4, s54, 0x6000
	s_addc_u32 s1, s93, s1
	s_add_i32 s4, s71, s4
	s_mov_b32 m0, s4
	s_waitcnt lgkmcnt(5)
	v_mfma_f32_32x32x16_bf16 v[64:79], v[160:163], v[124:127], v[64:79]
	global_load_lds_dwordx4 v176, s[0:1]
	s_add_i32 m0, s4, 0x400
	s_nop 0
	global_load_lds_dwordx4 v182, s[0:1]
	s_add_i32 m0, s4, 0x800
	s_nop 0
	global_load_lds_dwordx4 v184, s[0:1]
	v_mfma_f32_32x32x16_bf16 v[64:79], v[148:151], v[128:131], v[64:79]
	v_exp_f32_e32 v220, v88
	v_exp_f32_e32 v221, v89
	v_exp_f32_e32 v222, v90
	v_mfma_f32_32x32x16_bf16 v[64:79], v[156:159], v[132:135], v[64:79]
	v_exp_f32_e32 v223, v91
	v_add_f32_e32 v148, v220, v194
	v_add_f32_e32 v148, v221, v148
	v_add_f32_e32 v148, v222, v148
	v_add_f32_e32 v156, v223, v148
	v_cvt_pk_bf16_f32 v250, v220, v221
	v_cvt_pk_bf16_f32 v251, v222, v223
	v_mfma_f32_32x32x16_bf16 v[64:79], v[152:155], v[136:139], v[64:79]
	v_exp_f32_e32 v220, v92
	v_exp_f32_e32 v221, v93
	v_exp_f32_e32 v222, v94
	v_exp_f32_e32 v223, v95
	s_waitcnt lgkmcnt(0)
	v_mfma_f32_32x32x16_bf16 v[80:95], v[144:147], v[140:143], v[64:79]
	s_lshl_b64 s[0:1], s[48:49], 7
	s_add_u32 s0, s94, s0
	s_addc_u32 s1, s95, s1
	s_lshl_b32 s4, s53, 14
	s_add_i32 s4, s4, 0
	s_add_i32 s4, s4, s68
	s_add_i32 m0, s4, 0x12000
	s_nop 0
	global_load_lds_dwordx4 v186, s[0:1]
	s_add_i32 m0, s4, 0x12400
	s_nop 0
	global_load_lds_dwordx4 v188, s[0:1]
	v_mfma_f32_32x32x16_bf16 v[48:63], v[214:217], v[246:249], v[48:63]
	ds_read_b128 v[214:217], v245
	ds_read_b128 v[144:147], v245 offset:4096
	ds_read_b128 v[148:151], v245 offset:8192
	ds_read_b128 v[152:155], v245 offset:12288
	v_mfma_f32_32x32x16_bf16 v[32:47], v[164:167], v[246:249], v[32:47]
	v_add_f32_e32 v213, v220, v156
	v_add_f32_e32 v213, v221, v213
	v_add_f32_e32 v213, v222, v213
	v_add_f32_e32 v213, v223, v213
	v_add_f32_e32 v190, v190, v213
	v_mfma_f32_32x32x16_bf16 v[16:31], v[168:171], v[246:249], v[16:31]
	v_cvt_pk_bf16_f32 v252, v220, v221
	v_cvt_pk_bf16_f32 v253, v222, v223
	v_mfma_f32_32x32x16_bf16 v[0:15], v[172:175], v[246:249], v[0:15]
	s_waitcnt lgkmcnt(0)
	v_mfma_f32_32x32x16_bf16 v[48:63], v[214:217], v[250:253], v[48:63]
	s_waitcnt vmcnt(5) lgkmcnt(0)
	s_barrier
	s_add_i32 s52, s52, 1
	s_add_i32 s51, s51, 64
	s_cmp_eq_u32 s89, s52
	v_mfma_f32_32x32x16_bf16 v[32:47], v[144:147], v[250:253], v[32:47]
	v_mfma_f32_32x32x16_bf16 v[16:31], v[148:151], v[250:253], v[16:31]
	v_mfma_f32_32x32x16_bf16 v[0:15], v[152:155], v[250:253], v[0:15]
	s_cbranch_scc1 .LBB0_482
	s_mov_b32 s0, s84
	s_mov_b32 s84, s53
	s_mov_b32 s53, s54
	s_cmp_lt_i32 s51, 0
	s_mov_b32 s54, s0
	s_cbranch_scc0 .Latta_u1_476
	s_branch .Latta_u1_477

; #define LAS __attribute__((address_space(3)))
; __device__ __forceinline__ float max_xor32(float x) { const u32x2 r = __builtin_amdgcn_permlane32_swap(__float_as_uint(x), __float_as_uint(x), false, false); return fmaxf(__uint_as_float(r.x), __uint_as_float(r.y)); }
; #define MFMA32(a, b, c) __builtin_amdgcn_mfma_f32_32x32x16_bf16((a), (b), (c), 0, 0, 0)
; #define ATT_KRD(dst, g) do { _Pragma("unroll") for (int q_ = 0; q_ < 4; ++q_) dst[q_] = *(const LAS bf16x8*)(kb + kro[q_] + (g) * 128); } while (0)
; __device__ __forceinline__ void attn_unit(LAS unsigned char* lds, const bf16_t* Qg, const bf16_t* Kg, const bf16_t* Vtg, bf16_t* Og, int bh, int qb, int tid_, int wave, int lane_) {
;     ...
;     for (int j = 0; j < nt; ++j) {
;         const int relc = 64 * (j - 2 * qb) + 32 * kh - 32 * rg;
;         const int j3 = (j + 3 < nt) ? j + 3 : nt - 1, j2 = (j + 2 < nt) ? j + 2 : nt - 1;
;         const LAS unsigned char* kb = lds + KRING + s1 * KTILE;
;         const LAS unsigned char* vb = lds + s0 * VTILE;
;         if (relc >= 0) {
;             const int thr = (relc == 0) ? r : -1;
; #pragma unroll
;             for (int i = 0; i < 16; ++i) { const int key = (i & 3) + 8 * (i >> 2) + 4 * hi; if (key > thr) sc[i] = NINF; }
;         }
;     ...
;         bf16x8 fa[4], fb[4];
;         ATT_KRD(fa, 0); ATT_KRD(fb, 1);
; #pragma unroll
;         for (int i = 0; i < 16; ++i) sn[i] = 0.f;
;         float mx = sc[0];
; #pragma unroll
;         for (int i = 1; i < 16; ++i) mx = fmaxf(mx, sc[i]);
;         mx = max_xor32(mx);
; #pragma unroll
;         for (int q = 0; q < 4; ++q) sn = MFMA32(fa[q], qf[q], sn);
;         ATT_KRD(fa, 2);
;         __builtin_amdgcn_sched_barrier(0);
;         if (__builtin_amdgcn_ballot_w64(mx > mrun + 8.f) != 0ull) {
;             const float mnew = fmaxf(mrun, mx); const float alpha = __builtin_amdgcn_exp2f(mrun - mnew); mrun = mnew; lrun *= alpha;
; #pragma unroll
;             for (int dt = 0; dt < 4; ++dt) o[dt] = o[dt] * alpha;
;         }
.Latta_u1_477:
.Latta_u1_478:
	ds_read_b128 v[64:67], v191 offset:49152
	ds_read_b128 v[144:147], v197 offset:49152
	ds_read_b128 v[206:209], v200 offset:49152
	ds_read_b128 v[164:167], v191 offset:49280
	ds_read_b128 v[152:155], v199 offset:49152
	ds_read_b128 v[168:171], v199 offset:49280
	s_waitcnt lgkmcnt(0)
	v_mfma_f32_32x32x16_bf16 v[64:79], v[64:67], v[96:99], v[226:241]
	v_max_f32_e32 v149, v80, v81
	v_max3_f32 v157, v149, v82, v83
	ds_read_b128 v[148:151], v191 offset:49408
	s_waitcnt lgkmcnt(5)
	v_mfma_f32_32x32x16_bf16 v[64:79], v[144:147], v[100:103], v[64:79]
	v_max3_f32 v144, v157, v84, v85
	v_max3_f32 v144, v144, v86, v87
	v_max3_f32 v144, v144, v88, v89
	v_max3_f32 v144, v144, v90, v91
	v_max3_f32 v144, v144, v92, v93
	v_max3_f32 v193, v144, v94, v95
	s_waitcnt lgkmcnt(2)
	v_mfma_f32_32x32x16_bf16 v[64:79], v[152:155], v[104:107], v[64:79]
	ds_read_b128 v[172:175], v197 offset:49280
	ds_read_b128 v[156:159], v197 offset:49408
	ds_read_b128 v[152:155], v199 offset:49408
	ds_read_b128 v[160:163], v200 offset:49280
	ds_read_b128 v[144:147], v200 offset:49408
	v_mfma_f32_32x32x16_bf16 v[64:79], v[206:209], v[108:111], v[64:79]
	v_cmp_gt_f32_e32 vcc, v193, v242
	s_cbranch_vccz .Latta_u1_480
	v_mov_b32_e32 v194, v193
	s_nop 1
	v_permlane32_swap_b32_e32 v193, v194
	v_max_f32_e32 v205, v193, v194
	v_add_f32_e32 v192, v205, v243
	v_max_f32_e32 v193, v204, v204
	v_max_f32_e32 v193, v193, v192
	v_sub_f32_e32 v192, v204, v193
	v_sub_f32_e32 v244, v243, v193
	v_exp_f32_e32 v192, v192
	v_mov_b32_e32 v204, v193
	v_mov_b32_e32 v243, v193
	v_mov_b32_e32 v242, 0x41000000
	v_pk_mul_f32 v[62:63], v[62:63], v[192:193] op_sel_hi:[1,0]
	v_pk_mul_f32 v[60:61], v[60:61], v[192:193] op_sel_hi:[1,0]
	v_pk_mul_f32 v[58:59], v[58:59], v[192:193] op_sel_hi:[1,0]
	v_pk_mul_f32 v[56:57], v[56:57], v[192:193] op_sel_hi:[1,0]
	v_pk_mul_f32 v[54:55], v[54:55], v[192:193] op_sel_hi:[1,0]
	v_pk_mul_f32 v[52:53], v[52:53], v[192:193] op_sel_hi:[1,0]
	v_pk_mul_f32 v[50:51], v[50:51], v[192:193] op_sel_hi:[1,0]
	v_pk_mul_f32 v[48:49], v[48:49], v[192:193] op_sel_hi:[1,0]
	v_pk_mul_f32 v[46:47], v[46:47], v[192:193] op_sel_hi:[1,0]
	v_pk_mul_f32 v[44:45], v[44:45], v[192:193] op_sel_hi:[1,0]
	v_pk_mul_f32 v[42:43], v[42:43], v[192:193] op_sel_hi:[1,0]
	v_pk_mul_f32 v[40:41], v[40:41], v[192:193] op_sel_hi:[1,0]
	v_pk_mul_f32 v[38:39], v[38:39], v[192:193] op_sel_hi:[1,0]
	v_pk_mul_f32 v[36:37], v[36:37], v[192:193] op_sel_hi:[1,0]
	v_pk_mul_f32 v[34:35], v[34:35], v[192:193] op_sel_hi:[1,0]
	v_pk_mul_f32 v[32:33], v[32:33], v[192:193] op_sel_hi:[1,0]
	v_pk_mul_f32 v[30:31], v[30:31], v[192:193] op_sel_hi:[1,0]
	v_pk_mul_f32 v[28:29], v[28:29], v[192:193] op_sel_hi:[1,0]
	v_pk_mul_f32 v[26:27], v[26:27], v[192:193] op_sel_hi:[1,0]
	v_pk_mul_f32 v[24:25], v[24:25], v[192:193] op_sel_hi:[1,0]
	v_pk_mul_f32 v[22:23], v[22:23], v[192:193] op_sel_hi:[1,0]
	v_pk_mul_f32 v[20:21], v[20:21], v[192:193] op_sel_hi:[1,0]
	v_pk_mul_f32 v[18:19], v[18:19], v[192:193] op_sel_hi:[1,0]
	v_pk_mul_f32 v[16:17], v[16:17], v[192:193] op_sel_hi:[1,0]
	v_pk_mul_f32 v[14:15], v[14:15], v[192:193] op_sel_hi:[1,0]
	v_pk_mul_f32 v[12:13], v[12:13], v[192:193] op_sel_hi:[1,0]
	v_pk_mul_f32 v[10:11], v[10:11], v[192:193] op_sel_hi:[1,0]
	v_pk_mul_f32 v[8:9], v[8:9], v[192:193] op_sel_hi:[1,0]
	v_pk_mul_f32 v[6:7], v[6:7], v[192:193] op_sel_hi:[1,0]
	v_pk_mul_f32 v[4:5], v[4:5], v[192:193] op_sel_hi:[1,0]
	v_pk_mul_f32 v[2:3], v[2:3], v[192:193] op_sel_hi:[1,0]
	v_pk_mul_f32 v[0:1], v[0:1], v[192:193] op_sel_hi:[1,0]
	v_mul_f32_e32 v190, v190, v192
	v_add_f32_e32 v80, v80, v244
	v_add_f32_e32 v81, v81, v244
	v_add_f32_e32 v82, v82, v244
	v_add_f32_e32 v83, v83, v244
	v_add_f32_e32 v84, v84, v244
	v_add_f32_e32 v85, v85, v244
	v_add_f32_e32 v86, v86, v244
	v_add_f32_e32 v87, v87, v244
	v_add_f32_e32 v88, v88, v244
	v_add_f32_e32 v89, v89, v244
	v_add_f32_e32 v90, v90, v244
	v_add_f32_e32 v91, v91, v244
	v_add_f32_e32 v92, v92, v244
	v_add_f32_e32 v93, v93, v244
	v_add_f32_e32 v94, v94, v244
	v_add_f32_e32 v95, v95, v244
	v_add_f32_e32 v64, v64, v244
	v_add_f32_e32 v65, v65, v244
	v_add_f32_e32 v66, v66, v244
	v_add_f32_e32 v67, v67, v244
	v_add_f32_e32 v68, v68, v244
	v_add_f32_e32 v69, v69, v244
	v_add_f32_e32 v70, v70, v244
	v_add_f32_e32 v71, v71, v244
	v_add_f32_e32 v72, v72, v244
	v_add_f32_e32 v73, v73, v244
	v_add_f32_e32 v74, v74, v244
	v_add_f32_e32 v75, v75, v244
	v_add_f32_e32 v76, v76, v244
	v_add_f32_e32 v77, v77, v244
	v_add_f32_e32 v78, v78, v244
	v_add_f32_e32 v79, v79, v244
	v_sub_f32_e32 v226, 0, v193
	v_mov_b32_e32 v227, v226
	v_mov_b32_e32 v228, v226
	v_mov_b32_e32 v229, v226
	v_mov_b32_e32 v230, v226
	v_mov_b32_e32 v231, v226
	v_mov_b32_e32 v232, v226
	v_mov_b32_e32 v233, v226
	v_mov_b32_e32 v234, v226
	v_mov_b32_e32 v235, v226
	v_mov_b32_e32 v236, v226
	v_mov_b32_e32 v237, v226
	v_mov_b32_e32 v238, v226
	v_mov_b32_e32 v239, v226
	v_mov_b32_e32 v240, v226
	v_mov_b32_e32 v241, v226
; __device__ __forceinline__ unsigned pk2(float a, float b) { f32x2_t v = {a, b}; bf16x2v_t r = __builtin_convertvector(v, bf16x2v_t); return __builtin_bit_cast(unsigned, r); }
; __device__ __forceinline__ void attn_unit(LAS unsigned char* lds, const bf16_t* Qg, const bf16_t* Kg, const bf16_t* Vtg, bf16_t* Og, int bh, int qb, int tid_, int wave, int lane_) {
;     ...
;         float ps = 0.f; u32x4 p0, p1;
; #pragma unroll
;         for (int q = 0; q < 4; ++q) sn = MFMA32(fb[q], qf[4 + q], sn);
; #pragma unroll
;         for (int i = 0; i < 8; ++i) { sc[i] = __builtin_amdgcn_exp2f(sc[i] - mrun); ps += sc[i]; }
;         p0.x = pk2(sc[0], sc[1]); p0.y = pk2(sc[2], sc[3]); p0.z = pk2(sc[4], sc[5]); p0.w = pk2(sc[6], sc[7]);
;         __builtin_amdgcn_sched_barrier(0);
; #pragma unroll
;         for (int dt = 0; dt < 4; ++dt) fb[dt] = *(const LAS bf16x8*)(vb + vro[0] + dt * 4096);
;         __builtin_amdgcn_sched_barrier(0);
;         ATT_ISSUE_K(j3, s0);
;         __builtin_amdgcn_sched_barrier(0);
; #pragma unroll
;         for (int q = 0; q < 4; ++q) sn = MFMA32(fa[q], qf[8 + q], sn);
; #pragma unroll
;         for (int i = 8; i < 12; ++i) { sc[i] = __builtin_amdgcn_exp2f(sc[i] - mrun); ps += sc[i]; }
;         p1.x = pk2(sc[8], sc[9]); p1.y = pk2(sc[10], sc[11]);
;         __builtin_amdgcn_sched_barrier(0);
;         ATT_ISSUE_V(j2, s2);
;         __builtin_amdgcn_sched_barrier(0);
; #pragma unroll
;         for (int dt = 0; dt < 4; ++dt) fa[dt] = *(const LAS bf16x8*)(vb + vro[1] + dt * 4096);
;         { const bf16x8 pf0 = __builtin_bit_cast(bf16x8, p0);
;           o[0] = MFMA32(fb[0], pf0, o[0]); o[1] = MFMA32(fb[1], pf0, o[1]); o[2] = MFMA32(fb[2], pf0, o[2]); o[3] = MFMA32(fb[3], pf0, o[3]); }
; #pragma unroll
;         for (int i = 12; i < 16; ++i) { sc[i] = __builtin_amdgcn_exp2f(sc[i] - mrun); ps += sc[i]; }
;         p1.z = pk2(sc[12], sc[13]); p1.w = pk2(sc[14], sc[15]);
;         lrun += ps;
;         __builtin_amdgcn_sched_barrier(0);
;         { const bf16x8 pf1 = __builtin_bit_cast(bf16x8, p1);
;           o[0] = MFMA32(fa[0], pf1, o[0]); o[1] = MFMA32(fa[1], pf1, o[1]); o[2] = MFMA32(fa[2], pf1, o[2]); o[3] = MFMA32(fa[3], pf1, o[3]); }
;         asm volatile("s_waitcnt vmcnt(5) lgkmcnt(0)" ::: "memory"); __builtin_amdgcn_s_barrier(); asm volatile("" ::: "memory");
;         sc = sn;
;         { const int t = s0; s0 = s1; s1 = s2; s2 = t; }
;     }
.Latta_u1_480:
	v_mfma_f32_32x32x16_bf16 v[64:79], v[164:167], v[112:115], v[64:79]
	v_exp_f32_e32 v192, v80
	v_exp_f32_e32 v193, v81
	v_exp_f32_e32 v194, v82
	s_waitcnt lgkmcnt(0)
	v_mfma_f32_32x32x16_bf16 v[64:79], v[172:175], v[116:119], v[64:79]
	v_exp_f32_e32 v205, v83
	v_exp_f32_e32 v206, v84
	v_exp_f32_e32 v207, v85
	v_exp_f32_e32 v208, v86
	v_mfma_f32_32x32x16_bf16 v[64:79], v[168:171], v[120:123], v[64:79]
	s_add_i32 s0, s52, 3
	v_exp_f32_e32 v209, v87
	s_cmp_lt_u32 s0, s89
	s_cselect_b32 s0, s0, s45
	s_add_i32 s1, s52, 2
	s_cmp_lt_u32 s52, s44
	s_cselect_b32 s48, s1, s45
	v_cvt_pk_bf16_f32 v246, v192, v193
	v_cvt_pk_bf16_f32 v247, v194, v205
	v_cvt_pk_bf16_f32 v248, v206, v207
	v_cvt_pk_bf16_f32 v249, v208, v209
	ds_read_b128 v[214:217], v225 offset:16384
	ds_read_b128 v[164:167], v225 offset:20480
	ds_read_b128 v[168:171], v225 offset:24576
	ds_read_b128 v[172:175], v225 offset:28672
	v_add_f32_e32 v192, v193, v192
	v_add_f32_e32 v192, v194, v192
	v_add_f32_e32 v192, v205, v192
	v_add_f32_e32 v192, v206, v192
	v_add_f32_e32 v192, v207, v192
	v_add_f32_e32 v192, v208, v192
	v_add_f32_e32 v194, v209, v192
	s_mul_hi_u32 s1, s0, 0x6000
	s_mulk_i32 s0, 0x6000
	s_add_u32 s0, s92, s0
	s_mul_i32 s4, s54, 0x6000
	s_addc_u32 s1, s93, s1
	s_add_i32 s4, s71, s4
	s_mov_b32 m0, s4
	s_waitcnt lgkmcnt(5)
	v_mfma_f32_32x32x16_bf16 v[64:79], v[160:163], v[124:127], v[64:79]
	global_load_lds_dwordx4 v176, s[0:1]
	s_add_i32 m0, s4, 0x400
	s_nop 0
	global_load_lds_dwordx4 v182, s[0:1]
	s_add_i32 m0, s4, 0x800
	s_nop 0
	global_load_lds_dwordx4 v184, s[0:1]
	v_mfma_f32_32x32x16_bf16 v[64:79], v[148:151], v[128:131], v[64:79]
	v_exp_f32_e32 v220, v88
	v_exp_f32_e32 v221, v89
	v_exp_f32_e32 v222, v90
	v_mfma_f32_32x32x16_bf16 v[64:79], v[156:159], v[132:135], v[64:79]
	v_exp_f32_e32 v223, v91
	v_add_f32_e32 v148, v220, v194
	v_add_f32_e32 v148, v221, v148
	v_add_f32_e32 v148, v222, v148
	v_add_f32_e32 v156, v223, v148
	v_cvt_pk_bf16_f32 v250, v220, v221
	v_cvt_pk_bf16_f32 v251, v222, v223
	v_mfma_f32_32x32x16_bf16 v[64:79], v[152:155], v[136:139], v[64:79]
	v_exp_f32_e32 v220, v92
	v_exp_f32_e32 v221, v93
	v_exp_f32_e32 v222, v94
	v_exp_f32_e32 v223, v95
	s_waitcnt lgkmcnt(0)
	v_mfma_f32_32x32x16_bf16 v[80:95], v[144:147], v[140:143], v[64:79]
	s_lshl_b64 s[0:1], s[48:49], 7
	s_add_u32 s0, s94, s0
	s_addc_u32 s1, s95, s1
	s_lshl_b32 s4, s53, 14
	s_add_i32 s4, s4, 0
	s_add_i32 s4, s4, s68
	s_add_i32 m0, s4, 0x12000
	s_nop 0
	global_load_lds_dwordx4 v186, s[0:1]
	s_add_i32 m0, s4, 0x12400
	s_nop 0
	global_load_lds_dwordx4 v188, s[0:1]
	v_mfma_f32_32x32x16_bf16 v[48:63], v[214:217], v[246:249], v[48:63]
	ds_read_b128 v[214:217], v245 offset:16384
	ds_read_b128 v[144:147], v245 offset:20480
	ds_read_b128 v[148:151], v245 offset:24576
	ds_read_b128 v[152:155], v245 offset:28672
	v_mfma_f32_32x32x16_bf16 v[32:47], v[164:167], v[246:249], v[32:47]
	v_add_f32_e32 v213, v220, v156
	v_add_f32_e32 v213, v221, v213
	v_add_f32_e32 v213, v222, v213
	v_add_f32_e32 v213, v223, v213
	v_add_f32_e32 v190, v190, v213
	v_mfma_f32_32x32x16_bf16 v[16:31], v[168:171], v[246:249], v[16:31]
	v_cvt_pk_bf16_f32 v252, v220, v221
	v_cvt_pk_bf16_f32 v253, v222, v223
	v_mfma_f32_32x32x16_bf16 v[0:15], v[172:175], v[246:249], v[0:15]
	s_waitcnt lgkmcnt(0)
	v_mfma_f32_32x32x16_bf16 v[48:63], v[214:217], v[250:253], v[48:63]
	s_waitcnt vmcnt(5) lgkmcnt(0)
	s_barrier
	s_add_i32 s52, s52, 1
	s_add_i32 s51, s51, 64
	s_cmp_eq_u32 s89, s52
	v_mfma_f32_32x32x16_bf16 v[32:47], v[144:147], v[250:253], v[32:47]
	v_mfma_f32_32x32x16_bf16 v[16:31], v[148:151], v[250:253], v[16:31]
	v_mfma_f32_32x32x16_bf16 v[0:15], v[152:155], v[250:253], v[0:15]
	s_cbranch_scc1 .LBB0_482
	s_mov_b32 s0, s84
	s_mov_b32 s84, s53
	s_mov_b32 s53, s54
	s_cmp_lt_i32 s51, 0
	s_mov_b32 s54, s0
	s_cbranch_scc0 .Latta_u2_476
	s_branch .Latta_u2_477

; #define LAS __attribute__((address_space(3)))
; __device__ __forceinline__ float max_xor32(float x) { const u32x2 r = __builtin_amdgcn_permlane32_swap(__float_as_uint(x), __float_as_uint(x), false, false); return fmaxf(__uint_as_float(r.x), __uint_as_float(r.y)); }
; #define MFMA32(a, b, c) __builtin_amdgcn_mfma_f32_32x32x16_bf16((a), (b), (c), 0, 0, 0)
; #define ATT_KRD(dst, g) do { _Pragma("unroll") for (int q_ = 0; q_ < 4; ++q_) dst[q_] = *(const LAS bf16x8*)(kb + kro[q_] + (g) * 128); } while (0)
; __device__ __forceinline__ void attn_unit(LAS unsigned char* lds, const bf16_t* Qg, const bf16_t* Kg, const bf16_t* Vtg, bf16_t* Og, int bh, int qb, int tid_, int wave, int lane_) {
;     ...
;     for (int j = 0; j < nt; ++j) {
;         const int relc = 64 * (j - 2 * qb) + 32 * kh - 32 * rg;
;         const int j3 = (j + 3 < nt) ? j + 3 : nt - 1, j2 = (j + 2 < nt) ? j + 2 : nt - 1;
;         const LAS unsigned char* kb = lds + KRING + s1 * KTILE;
;         const LAS unsigned char* vb = lds + s0 * VTILE;
;         if (relc >= 0) {
;             const int thr = (relc == 0) ? r : -1;
; #pragma unroll
;             for (int i = 0; i < 16; ++i) { const int key = (i & 3) + 8 * (i >> 2) + 4 * hi; if (key > thr) sc[i] = NINF; }
;         }
;     ...
;         bf16x8 fa[4], fb[4];
;         ATT_KRD(fa, 0); ATT_KRD(fb, 1);
; #pragma unroll
;         for (int i = 0; i < 16; ++i) sn[i] = 0.f;
;         float mx = sc[0];
; #pragma unroll
;         for (int i = 1; i < 16; ++i) mx = fmaxf(mx, sc[i]);
;         mx = max_xor32(mx);
; #pragma unroll
;         for (int q = 0; q < 4; ++q) sn = MFMA32(fa[q], qf[q], sn);
;         ATT_KRD(fa, 2);
;         __builtin_amdgcn_sched_barrier(0);
;         if (__builtin_amdgcn_ballot_w64(mx > mrun + 8.f) != 0ull) {
;             const float mnew = fmaxf(mrun, mx); const float alpha = __builtin_amdgcn_exp2f(mrun - mnew); mrun = mnew; lrun *= alpha;
; #pragma unroll
;             for (int dt = 0; dt < 4; ++dt) o[dt] = o[dt] * alpha;
;         }
.Latta_u2_477:
.Latta_u2_478:
	ds_read_b128 v[64:67], v191
	ds_read_b128 v[144:147], v197
	ds_read_b128 v[206:209], v200
	ds_read_b128 v[164:167], v191 offset:128
	ds_read_b128 v[152:155], v199
	ds_read_b128 v[168:171], v199 offset:128
	s_waitcnt lgkmcnt(0)
	v_mfma_f32_32x32x16_bf16 v[64:79], v[64:67], v[96:99], v[226:241]
	v_max_f32_e32 v149, v80, v81
	v_max3_f32 v157, v149, v82, v83
	ds_read_b128 v[148:151], v191 offset:256
	s_waitcnt lgkmcnt(5)
	v_mfma_f32_32x32x16_bf16 v[64:79], v[144:147], v[100:103], v[64:79]
	v_max3_f32 v144, v157, v84, v85
	v_max3_f32 v144, v144, v86, v87
	v_max3_f32 v144, v144, v88, v89
	v_max3_f32 v144, v144, v90, v91
	v_max3_f32 v144, v144, v92, v93
	v_max3_f32 v193, v144, v94, v95
	s_waitcnt lgkmcnt(2)
	v_mfma_f32_32x32x16_bf16 v[64:79], v[152:155], v[104:107], v[64:79]
	ds_read_b128 v[172:175], v197 offset:128
	ds_read_b128 v[156:159], v197 offset:256
	ds_read_b128 v[152:155], v199 offset:256
	ds_read_b128 v[160:163], v200 offset:128
	ds_read_b128 v[144:147], v200 offset:256
	v_mfma_f32_32x32x16_bf16 v[64:79], v[206:209], v[108:111], v[64:79]
	v_cmp_gt_f32_e32 vcc, v193, v242
	s_cbranch_vccz .Latta_u2_480
	v_mov_b32_e32 v194, v193
	s_nop 1
	v_permlane32_swap_b32_e32 v193, v194
	v_max_f32_e32 v205, v193, v194
	v_add_f32_e32 v192, v205, v243
	v_max_f32_e32 v193, v204, v204
	v_max_f32_e32 v193, v193, v192
	v_sub_f32_e32 v192, v204, v193
	v_sub_f32_e32 v244, v243, v193
	v_exp_f32_e32 v192, v192
	v_mov_b32_e32 v204, v193
	v_mov_b32_e32 v243, v193
	v_mov_b32_e32 v242, 0x41000000
	v_pk_mul_f32 v[62:63], v[62:63], v[192:193] op_sel_hi:[1,0]
	v_pk_mul_f32 v[60:61], v[60:61], v[192:193] op_sel_hi:[1,0]
	v_pk_mul_f32 v[58:59], v[58:59], v[192:193] op_sel_hi:[1,0]
	v_pk_mul_f32 v[56:57], v[56:57], v[192:193] op_sel_hi:[1,0]
	v_pk_mul_f32 v[54:55], v[54:55], v[192:193] op_sel_hi:[1,0]
	v_pk_mul_f32 v[52:53], v[52:53], v[192:193] op_sel_hi:[1,0]
	v_pk_mul_f32 v[50:51], v[50:51], v[192:193] op_sel_hi:[1,0]
	v_pk_mul_f32 v[48:49], v[48:49], v[192:193] op_sel_hi:[1,0]
	v_pk_mul_f32 v[46:47], v[46:47], v[192:193] op_sel_hi:[1,0]
	v_pk_mul_f32 v[44:45], v[44:45], v[192:193] op_sel_hi:[1,0]
	v_pk_mul_f32 v[42:43], v[42:43], v[192:193] op_sel_hi:[1,0]
	v_pk_mul_f32 v[40:41], v[40:41], v[192:193] op_sel_hi:[1,0]
	v_pk_mul_f32 v[38:39], v[38:39], v[192:193] op_sel_hi:[1,0]
	v_pk_mul_f32 v[36:37], v[36:37], v[192:193] op_sel_hi:[1,0]
	v_pk_mul_f32 v[34:35], v[34:35], v[192:193] op_sel_hi:[1,0]
	v_pk_mul_f32 v[32:33], v[32:33], v[192:193] op_sel_hi:[1,0]
	v_pk_mul_f32 v[30:31], v[30:31], v[192:193] op_sel_hi:[1,0]
	v_pk_mul_f32 v[28:29], v[28:29], v[192:193] op_sel_hi:[1,0]
	v_pk_mul_f32 v[26:27], v[26:27], v[192:193] op_sel_hi:[1,0]
	v_pk_mul_f32 v[24:25], v[24:25], v[192:193] op_sel_hi:[1,0]
	v_pk_mul_f32 v[22:23], v[22:23], v[192:193] op_sel_hi:[1,0]
	v_pk_mul_f32 v[20:21], v[20:21], v[192:193] op_sel_hi:[1,0]
	v_pk_mul_f32 v[18:19], v[18:19], v[192:193] op_sel_hi:[1,0]
	v_pk_mul_f32 v[16:17], v[16:17], v[192:193] op_sel_hi:[1,0]
	v_pk_mul_f32 v[14:15], v[14:15], v[192:193] op_sel_hi:[1,0]
	v_pk_mul_f32 v[12:13], v[12:13], v[192:193] op_sel_hi:[1,0]
	v_pk_mul_f32 v[10:11], v[10:11], v[192:193] op_sel_hi:[1,0]
	v_pk_mul_f32 v[8:9], v[8:9], v[192:193] op_sel_hi:[1,0]
	v_pk_mul_f32 v[6:7], v[6:7], v[192:193] op_sel_hi:[1,0]
	v_pk_mul_f32 v[4:5], v[4:5], v[192:193] op_sel_hi:[1,0]
	v_pk_mul_f32 v[2:3], v[2:3], v[192:193] op_sel_hi:[1,0]
	v_pk_mul_f32 v[0:1], v[0:1], v[192:193] op_sel_hi:[1,0]
	v_mul_f32_e32 v190, v190, v192
	v_add_f32_e32 v80, v80, v244
	v_add_f32_e32 v81, v81, v244
	v_add_f32_e32 v82, v82, v244
	v_add_f32_e32 v83, v83, v244
	v_add_f32_e32 v84, v84, v244
	v_add_f32_e32 v85, v85, v244
	v_add_f32_e32 v86, v86, v244
	v_add_f32_e32 v87, v87, v244
	v_add_f32_e32 v88, v88, v244
	v_add_f32_e32 v89, v89, v244
	v_add_f32_e32 v90, v90, v244
	v_add_f32_e32 v91, v91, v244
	v_add_f32_e32 v92, v92, v244
	v_add_f32_e32 v93, v93, v244
	v_add_f32_e32 v94, v94, v244
	v_add_f32_e32 v95, v95, v244
	v_add_f32_e32 v64, v64, v244
	v_add_f32_e32 v65, v65, v244
	v_add_f32_e32 v66, v66, v244
	v_add_f32_e32 v67, v67, v244
	v_add_f32_e32 v68, v68, v244
	v_add_f32_e32 v69, v69, v244
	v_add_f32_e32 v70, v70, v244
	v_add_f32_e32 v71, v71, v244
	v_add_f32_e32 v72, v72, v244
	v_add_f32_e32 v73, v73, v244
	v_add_f32_e32 v74, v74, v244
	v_add_f32_e32 v75, v75, v244
	v_add_f32_e32 v76, v76, v244
	v_add_f32_e32 v77, v77, v244
	v_add_f32_e32 v78, v78, v244
	v_add_f32_e32 v79, v79, v244
	v_sub_f32_e32 v226, 0, v193
	v_mov_b32_e32 v227, v226
	v_mov_b32_e32 v228, v226
	v_mov_b32_e32 v229, v226
	v_mov_b32_e32 v230, v226
	v_mov_b32_e32 v231, v226
	v_mov_b32_e32 v232, v226
	v_mov_b32_e32 v233, v226
	v_mov_b32_e32 v234, v226
	v_mov_b32_e32 v235, v226
	v_mov_b32_e32 v236, v226
	v_mov_b32_e32 v237, v226
	v_mov_b32_e32 v238, v226
	v_mov_b32_e32 v239, v226
	v_mov_b32_e32 v240, v226
	v_mov_b32_e32 v241, v226
; __device__ __forceinline__ unsigned pk2(float a, float b) { f32x2_t v = {a, b}; bf16x2v_t r = __builtin_convertvector(v, bf16x2v_t); return __builtin_bit_cast(unsigned, r); }
; __device__ __forceinline__ void attn_unit(LAS unsigned char* lds, const bf16_t* Qg, const bf16_t* Kg, const bf16_t* Vtg, bf16_t* Og, int bh, int qb, int tid_, int wave, int lane_) {
;     ...
;         float ps = 0.f; u32x4 p0, p1;
; #pragma unroll
;         for (int q = 0; q < 4; ++q) sn = MFMA32(fb[q], qf[4 + q], sn);
; #pragma unroll
;         for (int i = 0; i < 8; ++i) { sc[i] = __builtin_amdgcn_exp2f(sc[i] - mrun); ps += sc[i]; }
;         p0.x = pk2(sc[0], sc[1]); p0.y = pk2(sc[2], sc[3]); p0.z = pk2(sc[4], sc[5]); p0.w = pk2(sc[6], sc[7]);
;         __builtin_amdgcn_sched_barrier(0);
; #pragma unroll
;         for (int dt = 0; dt < 4; ++dt) fb[dt] = *(const LAS bf16x8*)(vb + vro[0] + dt * 4096);
;         __builtin_amdgcn_sched_barrier(0);
;         ATT_ISSUE_K(j3, s0);
;         __builtin_amdgcn_sched_barrier(0);
; #pragma unroll
;         for (int q = 0; q < 4; ++q) sn = MFMA32(fa[q], qf[8 + q], sn);
; #pragma unroll
;         for (int i = 8; i < 12; ++i) { sc[i] = __builtin_amdgcn_exp2f(sc[i] - mrun); ps += sc[i]; }
;         p1.x = pk2(sc[8], sc[9]); p1.y = pk2(sc[10], sc[11]);
;         __builtin_amdgcn_sched_barrier(0);
;         ATT_ISSUE_V(j2, s2);
;         __builtin_amdgcn_sched_barrier(0);
; #pragma unroll
;         for (int dt = 0; dt < 4; ++dt) fa[dt] = *(const LAS bf16x8*)(vb + vro[1] + dt * 4096);
;         { const bf16x8 pf0 = __builtin_bit_cast(bf16x8, p0);
;           o[0] = MFMA32(fb[0], pf0, o[0]); o[1] = MFMA32(fb[1], pf0, o[1]); o[2] = MFMA32(fb[2], pf0, o[2]); o[3] = MFMA32(fb[3], pf0, o[3]); }
; #pragma unroll
;         for (int i = 12; i < 16; ++i) { sc[i] = __builtin_amdgcn_exp2f(sc[i] - mrun); ps += sc[i]; }
;         p1.z = pk2(sc[12], sc[13]); p1.w = pk2(sc[14], sc[15]);
;         lrun += ps;
;         __builtin_amdgcn_sched_barrier(0);
;         { const bf16x8 pf1 = __builtin_bit_cast(bf16x8, p1);
;           o[0] = MFMA32(fa[0], pf1, o[0]); o[1] = MFMA32(fa[1], pf1, o[1]); o[2] = MFMA32(fa[2], pf1, o[2]); o[3] = MFMA32(fa[3], pf1, o[3]); }
;         asm volatile("s_waitcnt vmcnt(5) lgkmcnt(0)" ::: "memory"); __builtin_amdgcn_s_barrier(); asm volatile("" ::: "memory");
;         sc = sn;
;         { const int t = s0; s0 = s1; s1 = s2; s2 = t; }
;     }
.Latta_u2_480:
	v_mfma_f32_32x32x16_bf16 v[64:79], v[164:167], v[112:115], v[64:79]
	v_exp_f32_e32 v192, v80
	v_exp_f32_e32 v193, v81
	v_exp_f32_e32 v194, v82
	s_waitcnt lgkmcnt(0)
	v_mfma_f32_32x32x16_bf16 v[64:79], v[172:175], v[116:119], v[64:79]
	v_exp_f32_e32 v205, v83
	v_exp_f32_e32 v206, v84
	v_exp_f32_e32 v207, v85
	v_exp_f32_e32 v208, v86
	v_mfma_f32_32x32x16_bf16 v[64:79], v[168:171], v[120:123], v[64:79]
	s_add_i32 s0, s52, 3
	v_exp_f32_e32 v209, v87
	s_cmp_lt_u32 s0, s89
	s_cselect_b32 s0, s0, s45
	s_add_i32 s1, s52, 2
	s_cmp_lt_u32 s52, s44
	s_cselect_b32 s48, s1, s45
	v_cvt_pk_bf16_f32 v246, v192, v193
	v_cvt_pk_bf16_f32 v247, v194, v205
	v_cvt_pk_bf16_f32 v248, v206, v207
	v_cvt_pk_bf16_f32 v249, v208, v209
	ds_read_b128 v[214:217], v225 offset:32768
	ds_read_b128 v[164:167], v225 offset:36864
	ds_read_b128 v[168:171], v225 offset:40960
	ds_read_b128 v[172:175], v225 offset:45056
	v_add_f32_e32 v192, v193, v192
	v_add_f32_e32 v192, v194, v192
	v_add_f32_e32 v192, v205, v192
	v_add_f32_e32 v192, v206, v192
	v_add_f32_e32 v192, v207, v192
	v_add_f32_e32 v192, v208, v192
	v_add_f32_e32 v194, v209, v192
	s_mul_hi_u32 s1, s0, 0x6000
	s_mulk_i32 s0, 0x6000
	s_add_u32 s0, s92, s0
	s_mul_i32 s4, s54, 0x6000
	s_addc_u32 s1, s93, s1
	s_add_i32 s4, s71, s4
	s_mov_b32 m0, s4
	s_waitcnt lgkmcnt(5)
	v_mfma_f32_32x32x16_bf16 v[64:79], v[160:163], v[124:127], v[64:79]
	global_load_lds_dwordx4 v176, s[0:1]
	s_add_i32 m0, s4, 0x400
	s_nop 0
	global_load_lds_dwordx4 v182, s[0:1]
	s_add_i32 m0, s4, 0x800
	s_nop 0
	global_load_lds_dwordx4 v184, s[0:1]
	v_mfma_f32_32x32x16_bf16 v[64:79], v[148:151], v[128:131], v[64:79]
	v_exp_f32_e32 v220, v88
	v_exp_f32_e32 v221, v89
	v_exp_f32_e32 v222, v90
	v_mfma_f32_32x32x16_bf16 v[64:79], v[156:159], v[132:135], v[64:79]
	v_exp_f32_e32 v223, v91
	v_add_f32_e32 v148, v220, v194
	v_add_f32_e32 v148, v221, v148
	v_add_f32_e32 v148, v222, v148
	v_add_f32_e32 v156, v223, v148
	v_cvt_pk_bf16_f32 v250, v220, v221
	v_cvt_pk_bf16_f32 v251, v222, v223
	v_mfma_f32_32x32x16_bf16 v[64:79], v[152:155], v[136:139], v[64:79]
	v_exp_f32_e32 v220, v92
	v_exp_f32_e32 v221, v93
	v_exp_f32_e32 v222, v94
	v_exp_f32_e32 v223, v95
	s_waitcnt lgkmcnt(0)
	v_mfma_f32_32x32x16_bf16 v[80:95], v[144:147], v[140:143], v[64:79]
	s_lshl_b64 s[0:1], s[48:49], 7
	s_add_u32 s0, s94, s0
	s_addc_u32 s1, s95, s1
	s_lshl_b32 s4, s53, 14
	s_add_i32 s4, s4, 0
	s_add_i32 s4, s4, s68
	s_add_i32 m0, s4, 0x12000
	s_nop 0
	global_load_lds_dwordx4 v186, s[0:1]
	s_add_i32 m0, s4, 0x12400
	s_nop 0
	global_load_lds_dwordx4 v188, s[0:1]
	v_mfma_f32_32x32x16_bf16 v[48:63], v[214:217], v[246:249], v[48:63]
	ds_read_b128 v[214:217], v245 offset:32768
	ds_read_b128 v[144:147], v245 offset:36864
	ds_read_b128 v[148:151], v245 offset:40960
	ds_read_b128 v[152:155], v245 offset:45056
	v_mfma_f32_32x32x16_bf16 v[32:47], v[164:167], v[246:249], v[32:47]
	v_add_f32_e32 v213, v220, v156
	v_add_f32_e32 v213, v221, v213
	v_add_f32_e32 v213, v222, v213
	v_add_f32_e32 v213, v223, v213
	v_add_f32_e32 v190, v190, v213
	v_mfma_f32_32x32x16_bf16 v[16:31], v[168:171], v[246:249], v[16:31]
	v_cvt_pk_bf16_f32 v252, v220, v221
	v_cvt_pk_bf16_f32 v253, v222, v223
	v_mfma_f32_32x32x16_bf16 v[0:15], v[172:175], v[246:249], v[0:15]
	s_waitcnt lgkmcnt(0)
	v_mfma_f32_32x32x16_bf16 v[48:63], v[214:217], v[250:253], v[48:63]
	s_waitcnt vmcnt(5) lgkmcnt(0)
	s_barrier
	s_add_i32 s52, s52, 1
	s_add_i32 s51, s51, 64
	s_cmp_eq_u32 s89, s52
	v_mfma_f32_32x32x16_bf16 v[32:47], v[144:147], v[250:253], v[32:47]
	v_mfma_f32_32x32x16_bf16 v[16:31], v[148:151], v[250:253], v[16:31]
	v_mfma_f32_32x32x16_bf16 v[0:15], v[152:155], v[250:253], v[0:15]
	s_cbranch_scc1 .LBB0_482
	s_mov_b32 s0, s84
	s_mov_b32 s84, s53
	s_mov_b32 s53, s54
	s_cmp_lt_i32 s51, 0
	s_mov_b32 s54, s0
	s_cbranch_scc0 .LBB0_476
	s_branch .LBB0_477

; #define LAS __attribute__((address_space(3)))
; __device__ __forceinline__ float max_xor32(float x) { const u32x2 r = __builtin_amdgcn_permlane32_swap(__float_as_uint(x), __float_as_uint(x), false, false); return fmaxf(__uint_as_float(r.x), __uint_as_float(r.y)); }
; #define MFMA32(a, b, c) __builtin_amdgcn_mfma_f32_32x32x16_bf16((a), (b), (c), 0, 0, 0)
; #define ATT_KRD(dst, g) do { _Pragma("unroll") for (int q_ = 0; q_ < 4; ++q_) dst[q_] = *(const LAS bf16x8*)(kb + kro[q_] + (g) * 128); } while (0)
; __device__ __forceinline__ void attn_unit(LAS unsigned char* lds, const bf16_t* Qg, const bf16_t* Kg, const bf16_t* Vtg, bf16_t* Og, int bh, int qb, int tid_, int wave, int lane_) {
;     ...
;     for (int j = 0; j < nt; ++j) {
;         const int relc = 64 * (j - 2 * qb) + 32 * kh - 32 * rg;
;         const int j3 = (j + 3 < nt) ? j + 3 : nt - 1, j2 = (j + 2 < nt) ? j + 2 : nt - 1;
;         const LAS unsigned char* kb = lds + KRING + s1 * KTILE;
;         const LAS unsigned char* vb = lds + s0 * VTILE;
;         if (relc >= 0) {
;             const int thr = (relc == 0) ? r : -1;
; #pragma unroll
;             for (int i = 0; i < 16; ++i) { const int key = (i & 3) + 8 * (i >> 2) + 4 * hi; if (key > thr) sc[i] = NINF; }
;         }
;     ...
;         bf16x8 fa[4], fb[4];
;         ATT_KRD(fa, 0); ATT_KRD(fb, 1);
; #pragma unroll
;         for (int i = 0; i < 16; ++i) sn[i] = 0.f;
;         float mx = sc[0];
; #pragma unroll
;         for (int i = 1; i < 16; ++i) mx = fmaxf(mx, sc[i]);
;         mx = max_xor32(mx);
; #pragma unroll
;         for (int q = 0; q < 4; ++q) sn = MFMA32(fa[q], qf[q], sn);
;         ATT_KRD(fa, 2);
;         __builtin_amdgcn_sched_barrier(0);
;         if (__builtin_amdgcn_ballot_w64(mx > mrun + 8.f) != 0ull) {
;             const float mnew = fmaxf(mrun, mx); const float alpha = __builtin_amdgcn_exp2f(mrun - mnew); mrun = mnew; lrun *= alpha;
; #pragma unroll
;             for (int dt = 0; dt < 4; ++dt) o[dt] = o[dt] * alpha;
;         }
;         float ps = 0.f; u32x4 p0, p1;
; #pragma unroll
;         for (int q = 0; q < 4; ++q) sn = MFMA32(fb[q], qf[4 + q], sn);
; #pragma unroll
.LBB0_489:
.LBB0_490:
	ds_read_b128 v[64:67], v199 offset:24576
	ds_read_b128 v[144:147], v200 offset:24576
	ds_read_b128 v[208:211], v202 offset:24576
	ds_read_b128 v[164:167], v199 offset:24704
	ds_read_b128 v[152:155], v201 offset:24576
	ds_read_b128 v[168:171], v201 offset:24704
	s_waitcnt lgkmcnt(0)
	v_mfma_f32_32x32x16_bf16 v[64:79], v[64:67], v[96:99], v[226:241]
	v_max_f32_e32 v149, v80, v81
	v_max3_f32 v157, v149, v82, v83
	ds_read_b128 v[148:151], v199 offset:24832
	s_waitcnt lgkmcnt(5)
	v_mfma_f32_32x32x16_bf16 v[64:79], v[144:147], v[100:103], v[64:79]
	v_max3_f32 v144, v157, v84, v85
	v_max3_f32 v144, v144, v86, v87
	v_max3_f32 v144, v144, v88, v89
	v_max3_f32 v144, v144, v90, v91
	v_max3_f32 v144, v144, v92, v93
	v_max3_f32 v193, v144, v94, v95
	s_waitcnt lgkmcnt(2)
	v_mfma_f32_32x32x16_bf16 v[64:79], v[152:155], v[104:107], v[64:79]
	ds_read_b128 v[172:175], v200 offset:24704
	ds_read_b128 v[156:159], v200 offset:24832
	ds_read_b128 v[152:155], v201 offset:24832
	ds_read_b128 v[160:163], v202 offset:24704
	ds_read_b128 v[144:147], v202 offset:24832
	v_mfma_f32_32x32x16_bf16 v[64:79], v[208:211], v[108:111], v[64:79]
	v_cmp_gt_f32_e32 vcc, v193, v242
	s_cbranch_vccz .LBB0_492
	v_mov_b32_e32 v194, v193
	s_nop 1
	v_permlane32_swap_b32_e32 v193, v194
	v_max_f32_e32 v207, v193, v194
	v_add_f32_e32 v192, v207, v243
	v_max_f32_e32 v193, v198, v198
	v_max_f32_e32 v193, v193, v192
	v_sub_f32_e32 v192, v198, v193
	v_sub_f32_e32 v244, v243, v193
	v_exp_f32_e32 v192, v192
	v_mov_b32_e32 v198, v193
	v_mov_b32_e32 v243, v193
	v_mov_b32_e32 v242, 0x41000000
	v_pk_mul_f32 v[62:63], v[62:63], v[192:193] op_sel_hi:[1,0]
	v_pk_mul_f32 v[60:61], v[60:61], v[192:193] op_sel_hi:[1,0]
	v_pk_mul_f32 v[58:59], v[58:59], v[192:193] op_sel_hi:[1,0]
	v_pk_mul_f32 v[56:57], v[56:57], v[192:193] op_sel_hi:[1,0]
	v_pk_mul_f32 v[54:55], v[54:55], v[192:193] op_sel_hi:[1,0]
	v_pk_mul_f32 v[52:53], v[52:53], v[192:193] op_sel_hi:[1,0]
	v_pk_mul_f32 v[50:51], v[50:51], v[192:193] op_sel_hi:[1,0]
	v_pk_mul_f32 v[48:49], v[48:49], v[192:193] op_sel_hi:[1,0]
	v_pk_mul_f32 v[46:47], v[46:47], v[192:193] op_sel_hi:[1,0]
	v_pk_mul_f32 v[44:45], v[44:45], v[192:193] op_sel_hi:[1,0]
	v_pk_mul_f32 v[42:43], v[42:43], v[192:193] op_sel_hi:[1,0]
	v_pk_mul_f32 v[40:41], v[40:41], v[192:193] op_sel_hi:[1,0]
	v_pk_mul_f32 v[38:39], v[38:39], v[192:193] op_sel_hi:[1,0]
	v_pk_mul_f32 v[36:37], v[36:37], v[192:193] op_sel_hi:[1,0]
	v_pk_mul_f32 v[34:35], v[34:35], v[192:193] op_sel_hi:[1,0]
	v_pk_mul_f32 v[32:33], v[32:33], v[192:193] op_sel_hi:[1,0]
	v_pk_mul_f32 v[30:31], v[30:31], v[192:193] op_sel_hi:[1,0]
	v_pk_mul_f32 v[28:29], v[28:29], v[192:193] op_sel_hi:[1,0]
	v_pk_mul_f32 v[26:27], v[26:27], v[192:193] op_sel_hi:[1,0]
	v_pk_mul_f32 v[24:25], v[24:25], v[192:193] op_sel_hi:[1,0]
	v_pk_mul_f32 v[22:23], v[22:23], v[192:193] op_sel_hi:[1,0]
	v_pk_mul_f32 v[20:21], v[20:21], v[192:193] op_sel_hi:[1,0]
	v_pk_mul_f32 v[18:19], v[18:19], v[192:193] op_sel_hi:[1,0]
	v_pk_mul_f32 v[16:17], v[16:17], v[192:193] op_sel_hi:[1,0]
	v_pk_mul_f32 v[14:15], v[14:15], v[192:193] op_sel_hi:[1,0]
	v_pk_mul_f32 v[12:13], v[12:13], v[192:193] op_sel_hi:[1,0]
	v_pk_mul_f32 v[10:11], v[10:11], v[192:193] op_sel_hi:[1,0]
	v_pk_mul_f32 v[8:9], v[8:9], v[192:193] op_sel_hi:[1,0]
	v_pk_mul_f32 v[6:7], v[6:7], v[192:193] op_sel_hi:[1,0]
	v_pk_mul_f32 v[4:5], v[4:5], v[192:193] op_sel_hi:[1,0]
	v_pk_mul_f32 v[2:3], v[2:3], v[192:193] op_sel_hi:[1,0]
	v_pk_mul_f32 v[0:1], v[0:1], v[192:193] op_sel_hi:[1,0]
	v_mul_f32_e32 v180, v180, v192
	v_add_f32_e32 v80, v80, v244
	v_add_f32_e32 v81, v81, v244
	v_add_f32_e32 v82, v82, v244
	v_add_f32_e32 v83, v83, v244
	v_add_f32_e32 v84, v84, v244
	v_add_f32_e32 v85, v85, v244
	v_add_f32_e32 v86, v86, v244
	v_add_f32_e32 v87, v87, v244
	v_add_f32_e32 v88, v88, v244
	v_add_f32_e32 v89, v89, v244
	v_add_f32_e32 v90, v90, v244
	v_add_f32_e32 v91, v91, v244
	v_add_f32_e32 v92, v92, v244
	v_add_f32_e32 v93, v93, v244
	v_add_f32_e32 v94, v94, v244
	v_add_f32_e32 v95, v95, v244
	v_add_f32_e32 v64, v64, v244
	v_add_f32_e32 v65, v65, v244
	v_add_f32_e32 v66, v66, v244
	v_add_f32_e32 v67, v67, v244
	v_add_f32_e32 v68, v68, v244
	v_add_f32_e32 v69, v69, v244
	v_add_f32_e32 v70, v70, v244
	v_add_f32_e32 v71, v71, v244
	v_add_f32_e32 v72, v72, v244
	v_add_f32_e32 v73, v73, v244
	v_add_f32_e32 v74, v74, v244
	v_add_f32_e32 v75, v75, v244
	v_add_f32_e32 v76, v76, v244
	v_add_f32_e32 v77, v77, v244
	v_add_f32_e32 v78, v78, v244
	v_add_f32_e32 v79, v79, v244
	v_sub_f32_e32 v226, 0, v193
	v_mov_b32_e32 v227, v226
	v_mov_b32_e32 v228, v226
	v_mov_b32_e32 v229, v226
	v_mov_b32_e32 v230, v226
	v_mov_b32_e32 v231, v226
	v_mov_b32_e32 v232, v226
	v_mov_b32_e32 v233, v226
	v_mov_b32_e32 v234, v226
	v_mov_b32_e32 v235, v226
	v_mov_b32_e32 v236, v226
	v_mov_b32_e32 v237, v226
	v_mov_b32_e32 v238, v226
	v_mov_b32_e32 v239, v226
	v_mov_b32_e32 v240, v226
	v_mov_b32_e32 v241, v226
; __device__ __forceinline__ unsigned pk2(float a, float b) { f32x2_t v = {a, b}; bf16x2v_t r = __builtin_convertvector(v, bf16x2v_t); return __builtin_bit_cast(unsigned, r); }
; __device__ __forceinline__ void attn_unit(LAS unsigned char* lds, const bf16_t* Qg, const bf16_t* Kg, const bf16_t* Vtg, bf16_t* Og, int bh, int qb, int tid_, int wave, int lane_) {
;     ...
;         float ps = 0.f; u32x4 p0, p1;
; #pragma unroll
;         for (int q = 0; q < 4; ++q) sn = MFMA32(fb[q], qf[4 + q], sn);
; #pragma unroll
;         for (int i = 0; i < 8; ++i) { sc[i] = __builtin_amdgcn_exp2f(sc[i] - mrun); ps += sc[i]; }
;         p0.x = pk2(sc[0], sc[1]); p0.y = pk2(sc[2], sc[3]); p0.z = pk2(sc[4], sc[5]); p0.w = pk2(sc[6], sc[7]);
;         __builtin_amdgcn_sched_barrier(0);
; #pragma unroll
;         for (int dt = 0; dt < 4; ++dt) fb[dt] = *(const LAS bf16x8*)(vb + vro[0] + dt * 4096);
;         __builtin_amdgcn_sched_barrier(0);
;         ATT_ISSUE_K(j3, s0);
;         __builtin_amdgcn_sched_barrier(0);
; #pragma unroll
;         for (int q = 0; q < 4; ++q) sn = MFMA32(fa[q], qf[8 + q], sn);
; #pragma unroll
;         for (int i = 8; i < 12; ++i) { sc[i] = __builtin_amdgcn_exp2f(sc[i] - mrun); ps += sc[i]; }
;         p1.x = pk2(sc[8], sc[9]); p1.y = pk2(sc[10], sc[11]);
;         __builtin_amdgcn_sched_barrier(0);
;         ATT_ISSUE_V(j2, s2);
;         __builtin_amdgcn_sched_barrier(0);
; #pragma unroll
;         for (int dt = 0; dt < 4; ++dt) fa[dt] = *(const LAS bf16x8*)(vb + vro[1] + dt * 4096);
;         { const bf16x8 pf0 = __builtin_bit_cast(bf16x8, p0);
;           o[0] = MFMA32(fb[0], pf0, o[0]); o[1] = MFMA32(fb[1], pf0, o[1]); o[2] = MFMA32(fb[2], pf0, o[2]); o[3] = MFMA32(fb[3], pf0, o[3]); }
; #pragma unroll
;         for (int i = 12; i < 16; ++i) { sc[i] = __builtin_amdgcn_exp2f(sc[i] - mrun); ps += sc[i]; }
;         p1.z = pk2(sc[12], sc[13]); p1.w = pk2(sc[14], sc[15]);
;         lrun += ps;
;         __builtin_amdgcn_sched_barrier(0);
;         { const bf16x8 pf1 = __builtin_bit_cast(bf16x8, p1);
;           o[0] = MFMA32(fa[0], pf1, o[0]); o[1] = MFMA32(fa[1], pf1, o[1]); o[2] = MFMA32(fa[2], pf1, o[2]); o[3] = MFMA32(fa[3], pf1, o[3]); }
;         asm volatile("s_waitcnt vmcnt(5) lgkmcnt(0)" ::: "memory"); __builtin_amdgcn_s_barrier(); asm volatile("" ::: "memory");
;         sc = sn;
;         { const int t = s0; s0 = s1; s1 = s2; s2 = t; }
;     }
.LBB0_492:
	v_mfma_f32_32x32x16_bf16 v[64:79], v[164:167], v[112:115], v[64:79]
	v_exp_f32_e32 v192, v80
	v_exp_f32_e32 v193, v81
	v_exp_f32_e32 v194, v82
	s_waitcnt lgkmcnt(0)
	v_mfma_f32_32x32x16_bf16 v[64:79], v[172:175], v[116:119], v[64:79]
	v_exp_f32_e32 v207, v83
	v_exp_f32_e32 v208, v84
	v_exp_f32_e32 v209, v85
	v_exp_f32_e32 v210, v86
	v_mfma_f32_32x32x16_bf16 v[64:79], v[168:171], v[120:123], v[64:79]
	s_add_i32 s0, s57, 3
	v_exp_f32_e32 v211, v87
	s_cmp_lt_i32 s0, s45
	s_cselect_b32 s0, s0, s44
	s_add_i32 s1, s57, 2
	s_cmp_lt_i32 s57, s52
	s_cselect_b32 s48, s1, s44
	v_cvt_pk_bf16_f32 v246, v192, v193
	v_cvt_pk_bf16_f32 v247, v194, v207
	v_cvt_pk_bf16_f32 v248, v208, v209
	v_cvt_pk_bf16_f32 v249, v210, v211
	ds_read_b128 v[214:217], v225
	ds_read_b128 v[164:167], v225 offset:4096
	ds_read_b128 v[168:171], v225 offset:8192
	ds_read_b128 v[172:175], v225 offset:12288
	v_add_f32_e32 v192, v193, v192
	v_add_f32_e32 v192, v194, v192
	v_add_f32_e32 v192, v207, v192
	v_add_f32_e32 v192, v208, v192
	v_add_f32_e32 v192, v209, v192
	v_add_f32_e32 v192, v210, v192
	v_add_f32_e32 v194, v211, v192
	s_mul_hi_u32 s1, s0, 0x6000
	s_mulk_i32 s0, 0x6000
	s_add_u32 s0, s92, s0
	s_mul_i32 s12, s58, 0x6000
	s_addc_u32 s1, s93, s1
	s_add_i32 s12, s71, s12
	s_mov_b32 m0, s12
	s_waitcnt lgkmcnt(5)
	v_mfma_f32_32x32x16_bf16 v[64:79], v[160:163], v[124:127], v[64:79]
	global_load_lds_dwordx4 v182, s[0:1]
	s_add_i32 m0, s12, 0x400
	s_nop 0
	global_load_lds_dwordx4 v184, s[0:1]
	s_add_i32 m0, s12, 0x800
	s_nop 0
	global_load_lds_dwordx4 v186, s[0:1]
	v_mfma_f32_32x32x16_bf16 v[64:79], v[148:151], v[128:131], v[64:79]
	v_exp_f32_e32 v220, v88
	v_exp_f32_e32 v221, v89
	v_exp_f32_e32 v222, v90
	v_mfma_f32_32x32x16_bf16 v[64:79], v[156:159], v[132:135], v[64:79]
	v_exp_f32_e32 v223, v91
	v_add_f32_e32 v148, v220, v194
	v_add_f32_e32 v148, v221, v148
	v_add_f32_e32 v148, v222, v148
	v_add_f32_e32 v156, v223, v148
	v_cvt_pk_bf16_f32 v250, v220, v221
	v_cvt_pk_bf16_f32 v251, v222, v223
	v_mfma_f32_32x32x16_bf16 v[64:79], v[152:155], v[136:139], v[64:79]
	v_exp_f32_e32 v220, v92
	v_exp_f32_e32 v221, v93
	v_exp_f32_e32 v222, v94
	v_exp_f32_e32 v223, v95
	s_waitcnt lgkmcnt(0)
	v_mfma_f32_32x32x16_bf16 v[80:95], v[144:147], v[140:143], v[64:79]
	s_lshl_b64 s[0:1], s[48:49], 7
	s_add_u32 s0, s94, s0
	s_addc_u32 s1, s95, s1
	s_lshl_b32 s12, s53, 14
	s_add_i32 s12, s12, 0
	s_add_i32 s12, s12, s68
	s_add_i32 m0, s12, 0x12000
	s_nop 0
	global_load_lds_dwordx4 v176, s[0:1]
	s_add_i32 m0, s12, 0x12400
	s_nop 0
	global_load_lds_dwordx4 v188, s[0:1]
	v_mfma_f32_32x32x16_bf16 v[48:63], v[214:217], v[246:249], v[48:63]
	ds_read_b128 v[214:217], v245
	ds_read_b128 v[144:147], v245 offset:4096
	ds_read_b128 v[148:151], v245 offset:8192
	ds_read_b128 v[152:155], v245 offset:12288
	v_mfma_f32_32x32x16_bf16 v[32:47], v[164:167], v[246:249], v[32:47]
	v_add_f32_e32 v213, v220, v156
	v_add_f32_e32 v213, v221, v213
	v_add_f32_e32 v213, v222, v213
	v_add_f32_e32 v213, v223, v213
	v_add_f32_e32 v180, v180, v213
	v_mfma_f32_32x32x16_bf16 v[16:31], v[168:171], v[246:249], v[16:31]
	v_cvt_pk_bf16_f32 v252, v220, v221
	v_cvt_pk_bf16_f32 v253, v222, v223
	v_mfma_f32_32x32x16_bf16 v[0:15], v[172:175], v[246:249], v[0:15]
	s_waitcnt lgkmcnt(0)
	v_mfma_f32_32x32x16_bf16 v[48:63], v[214:217], v[250:253], v[48:63]
	s_waitcnt vmcnt(5) lgkmcnt(0)
	s_barrier
	s_add_i32 s57, s57, 1
	s_add_i32 s56, s56, 64
	s_cmp_eq_u32 s45, s57
	v_mfma_f32_32x32x16_bf16 v[32:47], v[144:147], v[250:253], v[32:47]
	v_mfma_f32_32x32x16_bf16 v[16:31], v[148:151], v[250:253], v[16:31]
	v_mfma_f32_32x32x16_bf16 v[0:15], v[152:155], v[250:253], v[0:15]
	s_cbranch_scc1 .LBB0_495
	s_mov_b32 s0, s55
	s_mov_b32 s55, s53
	s_mov_b32 s53, s58
	s_add_i32 s1, s54, s56
	s_cmp_lt_i32 s1, 0
	s_mov_b32 s58, s0
	s_cbranch_scc0 .Lattb_u1_488
	s_branch .Lattb_u1_489

; #define LAS __attribute__((address_space(3)))
; __device__ __forceinline__ float max_xor32(float x) { const u32x2 r = __builtin_amdgcn_permlane32_swap(__float_as_uint(x), __float_as_uint(x), false, false); return fmaxf(__uint_as_float(r.x), __uint_as_float(r.y)); }
; #define MFMA32(a, b, c) __builtin_amdgcn_mfma_f32_32x32x16_bf16((a), (b), (c), 0, 0, 0)
; #define ATT_KRD(dst, g) do { _Pragma("unroll") for (int q_ = 0; q_ < 4; ++q_) dst[q_] = *(const LAS bf16x8*)(kb + kro[q_] + (g) * 128); } while (0)
; __device__ __forceinline__ void attn_unit(LAS unsigned char* lds, const bf16_t* Qg, const bf16_t* Kg, const bf16_t* Vtg, bf16_t* Og, int bh, int qb, int tid_, int wave, int lane_) {
;     ...
;     for (int j = 0; j < nt; ++j) {
;         const int relc = 64 * (j - 2 * qb) + 32 * kh - 32 * rg;
;         const int j3 = (j + 3 < nt) ? j + 3 : nt - 1, j2 = (j + 2 < nt) ? j + 2 : nt - 1;
;         const LAS unsigned char* kb = lds + KRING + s1 * KTILE;
;         const LAS unsigned char* vb = lds + s0 * VTILE;
;         if (relc >= 0) {
;             const int thr = (relc == 0) ? r : -1;
; #pragma unroll
;             for (int i = 0; i < 16; ++i) { const int key = (i & 3) + 8 * (i >> 2) + 4 * hi; if (key > thr) sc[i] = NINF; }
;         }
;     ...
;         bf16x8 fa[4], fb[4];
;         ATT_KRD(fa, 0); ATT_KRD(fb, 1);
; #pragma unroll
;         for (int i = 0; i < 16; ++i) sn[i] = 0.f;
;         float mx = sc[0];
; #pragma unroll
;         for (int i = 1; i < 16; ++i) mx = fmaxf(mx, sc[i]);
;         mx = max_xor32(mx);
; #pragma unroll
;         for (int q = 0; q < 4; ++q) sn = MFMA32(fa[q], qf[q], sn);
;         ATT_KRD(fa, 2);
;         __builtin_amdgcn_sched_barrier(0);
;         if (__builtin_amdgcn_ballot_w64(mx > mrun + 8.f) != 0ull) {
;             const float mnew = fmaxf(mrun, mx); const float alpha = __builtin_amdgcn_exp2f(mrun - mnew); mrun = mnew; lrun *= alpha;
; #pragma unroll
;             for (int dt = 0; dt < 4; ++dt) o[dt] = o[dt] * alpha;
;         }
.Lattb_u1_489:
.Lattb_u1_490:
	ds_read_b128 v[64:67], v199 offset:49152
	ds_read_b128 v[144:147], v200 offset:49152
	ds_read_b128 v[208:211], v202 offset:49152
	ds_read_b128 v[164:167], v199 offset:49280
	ds_read_b128 v[152:155], v201 offset:49152
	ds_read_b128 v[168:171], v201 offset:49280
	s_waitcnt lgkmcnt(0)
	v_mfma_f32_32x32x16_bf16 v[64:79], v[64:67], v[96:99], v[226:241]
	v_max_f32_e32 v149, v80, v81
	v_max3_f32 v157, v149, v82, v83
	ds_read_b128 v[148:151], v199 offset:49408
	s_waitcnt lgkmcnt(5)
	v_mfma_f32_32x32x16_bf16 v[64:79], v[144:147], v[100:103], v[64:79]
	v_max3_f32 v144, v157, v84, v85
	v_max3_f32 v144, v144, v86, v87
	v_max3_f32 v144, v144, v88, v89
	v_max3_f32 v144, v144, v90, v91
	v_max3_f32 v144, v144, v92, v93
	v_max3_f32 v193, v144, v94, v95
	s_waitcnt lgkmcnt(2)
	v_mfma_f32_32x32x16_bf16 v[64:79], v[152:155], v[104:107], v[64:79]
	ds_read_b128 v[172:175], v200 offset:49280
	ds_read_b128 v[156:159], v200 offset:49408
	ds_read_b128 v[152:155], v201 offset:49408
	ds_read_b128 v[160:163], v202 offset:49280
	ds_read_b128 v[144:147], v202 offset:49408
	v_mfma_f32_32x32x16_bf16 v[64:79], v[208:211], v[108:111], v[64:79]
	v_cmp_gt_f32_e32 vcc, v193, v242
	s_cbranch_vccz .Lattb_u1_492
	v_mov_b32_e32 v194, v193
	s_nop 1
	v_permlane32_swap_b32_e32 v193, v194
	v_max_f32_e32 v207, v193, v194
	v_add_f32_e32 v192, v207, v243
	v_max_f32_e32 v193, v198, v198
	v_max_f32_e32 v193, v193, v192
	v_sub_f32_e32 v192, v198, v193
	v_sub_f32_e32 v244, v243, v193
	v_exp_f32_e32 v192, v192
	v_mov_b32_e32 v198, v193
	v_mov_b32_e32 v243, v193
	v_mov_b32_e32 v242, 0x41000000
	v_pk_mul_f32 v[62:63], v[62:63], v[192:193] op_sel_hi:[1,0]
	v_pk_mul_f32 v[60:61], v[60:61], v[192:193] op_sel_hi:[1,0]
	v_pk_mul_f32 v[58:59], v[58:59], v[192:193] op_sel_hi:[1,0]
	v_pk_mul_f32 v[56:57], v[56:57], v[192:193] op_sel_hi:[1,0]
	v_pk_mul_f32 v[54:55], v[54:55], v[192:193] op_sel_hi:[1,0]
	v_pk_mul_f32 v[52:53], v[52:53], v[192:193] op_sel_hi:[1,0]
	v_pk_mul_f32 v[50:51], v[50:51], v[192:193] op_sel_hi:[1,0]
	v_pk_mul_f32 v[48:49], v[48:49], v[192:193] op_sel_hi:[1,0]
	v_pk_mul_f32 v[46:47], v[46:47], v[192:193] op_sel_hi:[1,0]
	v_pk_mul_f32 v[44:45], v[44:45], v[192:193] op_sel_hi:[1,0]
	v_pk_mul_f32 v[42:43], v[42:43], v[192:193] op_sel_hi:[1,0]
	v_pk_mul_f32 v[40:41], v[40:41], v[192:193] op_sel_hi:[1,0]
	v_pk_mul_f32 v[38:39], v[38:39], v[192:193] op_sel_hi:[1,0]
	v_pk_mul_f32 v[36:37], v[36:37], v[192:193] op_sel_hi:[1,0]
	v_pk_mul_f32 v[34:35], v[34:35], v[192:193] op_sel_hi:[1,0]
	v_pk_mul_f32 v[32:33], v[32:33], v[192:193] op_sel_hi:[1,0]
	v_pk_mul_f32 v[30:31], v[30:31], v[192:193] op_sel_hi:[1,0]
	v_pk_mul_f32 v[28:29], v[28:29], v[192:193] op_sel_hi:[1,0]
	v_pk_mul_f32 v[26:27], v[26:27], v[192:193] op_sel_hi:[1,0]
	v_pk_mul_f32 v[24:25], v[24:25], v[192:193] op_sel_hi:[1,0]
	v_pk_mul_f32 v[22:23], v[22:23], v[192:193] op_sel_hi:[1,0]
	v_pk_mul_f32 v[20:21], v[20:21], v[192:193] op_sel_hi:[1,0]
	v_pk_mul_f32 v[18:19], v[18:19], v[192:193] op_sel_hi:[1,0]
	v_pk_mul_f32 v[16:17], v[16:17], v[192:193] op_sel_hi:[1,0]
	v_pk_mul_f32 v[14:15], v[14:15], v[192:193] op_sel_hi:[1,0]
	v_pk_mul_f32 v[12:13], v[12:13], v[192:193] op_sel_hi:[1,0]
	v_pk_mul_f32 v[10:11], v[10:11], v[192:193] op_sel_hi:[1,0]
	v_pk_mul_f32 v[8:9], v[8:9], v[192:193] op_sel_hi:[1,0]
	v_pk_mul_f32 v[6:7], v[6:7], v[192:193] op_sel_hi:[1,0]
	v_pk_mul_f32 v[4:5], v[4:5], v[192:193] op_sel_hi:[1,0]
	v_pk_mul_f32 v[2:3], v[2:3], v[192:193] op_sel_hi:[1,0]
	v_pk_mul_f32 v[0:1], v[0:1], v[192:193] op_sel_hi:[1,0]
	v_mul_f32_e32 v180, v180, v192
	v_add_f32_e32 v80, v80, v244
	v_add_f32_e32 v81, v81, v244
	v_add_f32_e32 v82, v82, v244
	v_add_f32_e32 v83, v83, v244
	v_add_f32_e32 v84, v84, v244
	v_add_f32_e32 v85, v85, v244
	v_add_f32_e32 v86, v86, v244
	v_add_f32_e32 v87, v87, v244
	v_add_f32_e32 v88, v88, v244
	v_add_f32_e32 v89, v89, v244
	v_add_f32_e32 v90, v90, v244
	v_add_f32_e32 v91, v91, v244
	v_add_f32_e32 v92, v92, v244
	v_add_f32_e32 v93, v93, v244
	v_add_f32_e32 v94, v94, v244
	v_add_f32_e32 v95, v95, v244
	v_add_f32_e32 v64, v64, v244
	v_add_f32_e32 v65, v65, v244
	v_add_f32_e32 v66, v66, v244
	v_add_f32_e32 v67, v67, v244
	v_add_f32_e32 v68, v68, v244
	v_add_f32_e32 v69, v69, v244
	v_add_f32_e32 v70, v70, v244
	v_add_f32_e32 v71, v71, v244
	v_add_f32_e32 v72, v72, v244
	v_add_f32_e32 v73, v73, v244
	v_add_f32_e32 v74, v74, v244
	v_add_f32_e32 v75, v75, v244
	v_add_f32_e32 v76, v76, v244
	v_add_f32_e32 v77, v77, v244
	v_add_f32_e32 v78, v78, v244
	v_add_f32_e32 v79, v79, v244
	v_sub_f32_e32 v226, 0, v193
	v_mov_b32_e32 v227, v226
	v_mov_b32_e32 v228, v226
	v_mov_b32_e32 v229, v226
	v_mov_b32_e32 v230, v226
	v_mov_b32_e32 v231, v226
	v_mov_b32_e32 v232, v226
	v_mov_b32_e32 v233, v226
	v_mov_b32_e32 v234, v226
	v_mov_b32_e32 v235, v226
	v_mov_b32_e32 v236, v226
	v_mov_b32_e32 v237, v226
	v_mov_b32_e32 v238, v226
	v_mov_b32_e32 v239, v226
	v_mov_b32_e32 v240, v226
	v_mov_b32_e32 v241, v226
; __device__ __forceinline__ unsigned pk2(float a, float b) { f32x2_t v = {a, b}; bf16x2v_t r = __builtin_convertvector(v, bf16x2v_t); return __builtin_bit_cast(unsigned, r); }
; __device__ __forceinline__ void attn_unit(LAS unsigned char* lds, const bf16_t* Qg, const bf16_t* Kg, const bf16_t* Vtg, bf16_t* Og, int bh, int qb, int tid_, int wave, int lane_) {
;     ...
;         float ps = 0.f; u32x4 p0, p1;
; #pragma unroll
;         for (int q = 0; q < 4; ++q) sn = MFMA32(fb[q], qf[4 + q], sn);
; #pragma unroll
;         for (int i = 0; i < 8; ++i) { sc[i] = __builtin_amdgcn_exp2f(sc[i] - mrun); ps += sc[i]; }
;         p0.x = pk2(sc[0], sc[1]); p0.y = pk2(sc[2], sc[3]); p0.z = pk2(sc[4], sc[5]); p0.w = pk2(sc[6], sc[7]);
;         __builtin_amdgcn_sched_barrier(0);
; #pragma unroll
;         for (int dt = 0; dt < 4; ++dt) fb[dt] = *(const LAS bf16x8*)(vb + vro[0] + dt * 4096);
;         __builtin_amdgcn_sched_barrier(0);
;         ATT_ISSUE_K(j3, s0);
;         __builtin_amdgcn_sched_barrier(0);
; #pragma unroll
;         for (int q = 0; q < 4; ++q) sn = MFMA32(fa[q], qf[8 + q], sn);
; #pragma unroll
;         for (int i = 8; i < 12; ++i) { sc[i] = __builtin_amdgcn_exp2f(sc[i] - mrun); ps += sc[i]; }
;         p1.x = pk2(sc[8], sc[9]); p1.y = pk2(sc[10], sc[11]);
;         __builtin_amdgcn_sched_barrier(0);
;         ATT_ISSUE_V(j2, s2);
;         __builtin_amdgcn_sched_barrier(0);
; #pragma unroll
;         for (int dt = 0; dt < 4; ++dt) fa[dt] = *(const LAS bf16x8*)(vb + vro[1] + dt * 4096);
;         { const bf16x8 pf0 = __builtin_bit_cast(bf16x8, p0);
;           o[0] = MFMA32(fb[0], pf0, o[0]); o[1] = MFMA32(fb[1], pf0, o[1]); o[2] = MFMA32(fb[2], pf0, o[2]); o[3] = MFMA32(fb[3], pf0, o[3]); }
; #pragma unroll
;         for (int i = 12; i < 16; ++i) { sc[i] = __builtin_amdgcn_exp2f(sc[i] - mrun); ps += sc[i]; }
;         p1.z = pk2(sc[12], sc[13]); p1.w = pk2(sc[14], sc[15]);
;         lrun += ps;
;         __builtin_amdgcn_sched_barrier(0);
;         { const bf16x8 pf1 = __builtin_bit_cast(bf16x8, p1);
;           o[0] = MFMA32(fa[0], pf1, o[0]); o[1] = MFMA32(fa[1], pf1, o[1]); o[2] = MFMA32(fa[2], pf1, o[2]); o[3] = MFMA32(fa[3], pf1, o[3]); }
;         asm volatile("s_waitcnt vmcnt(5) lgkmcnt(0)" ::: "memory"); __builtin_amdgcn_s_barrier(); asm volatile("" ::: "memory");
;         sc = sn;
;         { const int t = s0; s0 = s1; s1 = s2; s2 = t; }
;     }
.Lattb_u1_492:
	v_mfma_f32_32x32x16_bf16 v[64:79], v[164:167], v[112:115], v[64:79]
	v_exp_f32_e32 v192, v80
	v_exp_f32_e32 v193, v81
	v_exp_f32_e32 v194, v82
	s_waitcnt lgkmcnt(0)
	v_mfma_f32_32x32x16_bf16 v[64:79], v[172:175], v[116:119], v[64:79]
	v_exp_f32_e32 v207, v83
	v_exp_f32_e32 v208, v84
	v_exp_f32_e32 v209, v85
	v_exp_f32_e32 v210, v86
	v_mfma_f32_32x32x16_bf16 v[64:79], v[168:171], v[120:123], v[64:79]
	s_add_i32 s0, s57, 3
	v_exp_f32_e32 v211, v87
	s_cmp_lt_i32 s0, s45
	s_cselect_b32 s0, s0, s44
	s_add_i32 s1, s57, 2
	s_cmp_lt_i32 s57, s52
	s_cselect_b32 s48, s1, s44
	v_cvt_pk_bf16_f32 v246, v192, v193
	v_cvt_pk_bf16_f32 v247, v194, v207
	v_cvt_pk_bf16_f32 v248, v208, v209
	v_cvt_pk_bf16_f32 v249, v210, v211
	ds_read_b128 v[214:217], v225 offset:16384
	ds_read_b128 v[164:167], v225 offset:20480
	ds_read_b128 v[168:171], v225 offset:24576
	ds_read_b128 v[172:175], v225 offset:28672
	v_add_f32_e32 v192, v193, v192
	v_add_f32_e32 v192, v194, v192
	v_add_f32_e32 v192, v207, v192
	v_add_f32_e32 v192, v208, v192
	v_add_f32_e32 v192, v209, v192
	v_add_f32_e32 v192, v210, v192
	v_add_f32_e32 v194, v211, v192
	s_mul_hi_u32 s1, s0, 0x6000
	s_mulk_i32 s0, 0x6000
	s_add_u32 s0, s92, s0
	s_mul_i32 s12, s58, 0x6000
	s_addc_u32 s1, s93, s1
	s_add_i32 s12, s71, s12
	s_mov_b32 m0, s12
	s_waitcnt lgkmcnt(5)
	v_mfma_f32_32x32x16_bf16 v[64:79], v[160:163], v[124:127], v[64:79]
	global_load_lds_dwordx4 v182, s[0:1]
	s_add_i32 m0, s12, 0x400
	s_nop 0
	global_load_lds_dwordx4 v184, s[0:1]
	s_add_i32 m0, s12, 0x800
	s_nop 0
	global_load_lds_dwordx4 v186, s[0:1]
	v_mfma_f32_32x32x16_bf16 v[64:79], v[148:151], v[128:131], v[64:79]
	v_exp_f32_e32 v220, v88
	v_exp_f32_e32 v221, v89
	v_exp_f32_e32 v222, v90
	v_mfma_f32_32x32x16_bf16 v[64:79], v[156:159], v[132:135], v[64:79]
	v_exp_f32_e32 v223, v91
	v_add_f32_e32 v148, v220, v194
	v_add_f32_e32 v148, v221, v148
	v_add_f32_e32 v148, v222, v148
	v_add_f32_e32 v156, v223, v148
	v_cvt_pk_bf16_f32 v250, v220, v221
	v_cvt_pk_bf16_f32 v251, v222, v223
	v_mfma_f32_32x32x16_bf16 v[64:79], v[152:155], v[136:139], v[64:79]
	v_exp_f32_e32 v220, v92
	v_exp_f32_e32 v221, v93
	v_exp_f32_e32 v222, v94
	v_exp_f32_e32 v223, v95
	s_waitcnt lgkmcnt(0)
	v_mfma_f32_32x32x16_bf16 v[80:95], v[144:147], v[140:143], v[64:79]
	s_lshl_b64 s[0:1], s[48:49], 7
	s_add_u32 s0, s94, s0
	s_addc_u32 s1, s95, s1
	s_lshl_b32 s12, s53, 14
	s_add_i32 s12, s12, 0
	s_add_i32 s12, s12, s68
	s_add_i32 m0, s12, 0x12000
	s_nop 0
	global_load_lds_dwordx4 v176, s[0:1]
	s_add_i32 m0, s12, 0x12400
	s_nop 0
	global_load_lds_dwordx4 v188, s[0:1]
	v_mfma_f32_32x32x16_bf16 v[48:63], v[214:217], v[246:249], v[48:63]
	ds_read_b128 v[214:217], v245 offset:16384
	ds_read_b128 v[144:147], v245 offset:20480
	ds_read_b128 v[148:151], v245 offset:24576
	ds_read_b128 v[152:155], v245 offset:28672
	v_mfma_f32_32x32x16_bf16 v[32:47], v[164:167], v[246:249], v[32:47]
	v_add_f32_e32 v213, v220, v156
	v_add_f32_e32 v213, v221, v213
	v_add_f32_e32 v213, v222, v213
	v_add_f32_e32 v213, v223, v213
	v_add_f32_e32 v180, v180, v213
	v_mfma_f32_32x32x16_bf16 v[16:31], v[168:171], v[246:249], v[16:31]
	v_cvt_pk_bf16_f32 v252, v220, v221
	v_cvt_pk_bf16_f32 v253, v222, v223
	v_mfma_f32_32x32x16_bf16 v[0:15], v[172:175], v[246:249], v[0:15]
	s_waitcnt lgkmcnt(0)
	v_mfma_f32_32x32x16_bf16 v[48:63], v[214:217], v[250:253], v[48:63]
	s_waitcnt vmcnt(5) lgkmcnt(0)
	s_barrier
	s_add_i32 s57, s57, 1
	s_add_i32 s56, s56, 64
	s_cmp_eq_u32 s45, s57
	v_mfma_f32_32x32x16_bf16 v[32:47], v[144:147], v[250:253], v[32:47]
	v_mfma_f32_32x32x16_bf16 v[16:31], v[148:151], v[250:253], v[16:31]
	v_mfma_f32_32x32x16_bf16 v[0:15], v[152:155], v[250:253], v[0:15]
	s_cbranch_scc1 .LBB0_495
	s_mov_b32 s0, s55
	s_mov_b32 s55, s53
	s_mov_b32 s53, s58
	s_add_i32 s1, s54, s56
	s_cmp_lt_i32 s1, 0
	s_mov_b32 s58, s0
	s_cbranch_scc0 .Lattb_u2_488
	s_branch .Lattb_u2_489

; #define LAS __attribute__((address_space(3)))
; __device__ __forceinline__ float max_xor32(float x) { const u32x2 r = __builtin_amdgcn_permlane32_swap(__float_as_uint(x), __float_as_uint(x), false, false); return fmaxf(__uint_as_float(r.x), __uint_as_float(r.y)); }
; #define MFMA32(a, b, c) __builtin_amdgcn_mfma_f32_32x32x16_bf16((a), (b), (c), 0, 0, 0)
; #define ATT_KRD(dst, g) do { _Pragma("unroll") for (int q_ = 0; q_ < 4; ++q_) dst[q_] = *(const LAS bf16x8*)(kb + kro[q_] + (g) * 128); } while (0)
; __device__ __forceinline__ void attn_unit(LAS unsigned char* lds, const bf16_t* Qg, const bf16_t* Kg, const bf16_t* Vtg, bf16_t* Og, int bh, int qb, int tid_, int wave, int lane_) {
;     ...
;     for (int j = 0; j < nt; ++j) {
;         const int relc = 64 * (j - 2 * qb) + 32 * kh - 32 * rg;
;         const int j3 = (j + 3 < nt) ? j + 3 : nt - 1, j2 = (j + 2 < nt) ? j + 2 : nt - 1;
;         const LAS unsigned char* kb = lds + KRING + s1 * KTILE;
;         const LAS unsigned char* vb = lds + s0 * VTILE;
;         if (relc >= 0) {
;             const int thr = (relc == 0) ? r : -1;
; #pragma unroll
;             for (int i = 0; i < 16; ++i) { const int key = (i & 3) + 8 * (i >> 2) + 4 * hi; if (key > thr) sc[i] = NINF; }
;         }
;     ...
;         bf16x8 fa[4], fb[4];
;         ATT_KRD(fa, 0); ATT_KRD(fb, 1);
; #pragma unroll
;         for (int i = 0; i < 16; ++i) sn[i] = 0.f;
;         float mx = sc[0];
; #pragma unroll
;         for (int i = 1; i < 16; ++i) mx = fmaxf(mx, sc[i]);
;         mx = max_xor32(mx);
; #pragma unroll
;         for (int q = 0; q < 4; ++q) sn = MFMA32(fa[q], qf[q], sn);
;         ATT_KRD(fa, 2);
;         __builtin_amdgcn_sched_barrier(0);
;         if (__builtin_amdgcn_ballot_w64(mx > mrun + 8.f) != 0ull) {
;             const float mnew = fmaxf(mrun, mx); const float alpha = __builtin_amdgcn_exp2f(mrun - mnew); mrun = mnew; lrun *= alpha;
; #pragma unroll
;             for (int dt = 0; dt < 4; ++dt) o[dt] = o[dt] * alpha;
;         }
.Lattb_u2_489:
.Lattb_u2_490:
	ds_read_b128 v[64:67], v199
	ds_read_b128 v[144:147], v200
	ds_read_b128 v[208:211], v202
	ds_read_b128 v[164:167], v199 offset:128
	ds_read_b128 v[152:155], v201
	ds_read_b128 v[168:171], v201 offset:128
	s_waitcnt lgkmcnt(0)
	v_mfma_f32_32x32x16_bf16 v[64:79], v[64:67], v[96:99], v[226:241]
	v_max_f32_e32 v149, v80, v81
	v_max3_f32 v157, v149, v82, v83
	ds_read_b128 v[148:151], v199 offset:256
	s_waitcnt lgkmcnt(5)
	v_mfma_f32_32x32x16_bf16 v[64:79], v[144:147], v[100:103], v[64:79]
	v_max3_f32 v144, v157, v84, v85
	v_max3_f32 v144, v144, v86, v87
	v_max3_f32 v144, v144, v88, v89
	v_max3_f32 v144, v144, v90, v91
	v_max3_f32 v144, v144, v92, v93
	v_max3_f32 v193, v144, v94, v95
	s_waitcnt lgkmcnt(2)
	v_mfma_f32_32x32x16_bf16 v[64:79], v[152:155], v[104:107], v[64:79]
	ds_read_b128 v[172:175], v200 offset:128
	ds_read_b128 v[156:159], v200 offset:256
	ds_read_b128 v[152:155], v201 offset:256
	ds_read_b128 v[160:163], v202 offset:128
	ds_read_b128 v[144:147], v202 offset:256
	v_mfma_f32_32x32x16_bf16 v[64:79], v[208:211], v[108:111], v[64:79]
	v_cmp_gt_f32_e32 vcc, v193, v242
	s_cbranch_vccz .Lattb_u2_492
	v_mov_b32_e32 v194, v193
	s_nop 1
	v_permlane32_swap_b32_e32 v193, v194
	v_max_f32_e32 v207, v193, v194
	v_add_f32_e32 v192, v207, v243
	v_max_f32_e32 v193, v198, v198
	v_max_f32_e32 v193, v193, v192
	v_sub_f32_e32 v192, v198, v193
	v_sub_f32_e32 v244, v243, v193
	v_exp_f32_e32 v192, v192
	v_mov_b32_e32 v198, v193
	v_mov_b32_e32 v243, v193
	v_mov_b32_e32 v242, 0x41000000
	v_pk_mul_f32 v[62:63], v[62:63], v[192:193] op_sel_hi:[1,0]
	v_pk_mul_f32 v[60:61], v[60:61], v[192:193] op_sel_hi:[1,0]
	v_pk_mul_f32 v[58:59], v[58:59], v[192:193] op_sel_hi:[1,0]
	v_pk_mul_f32 v[56:57], v[56:57], v[192:193] op_sel_hi:[1,0]
	v_pk_mul_f32 v[54:55], v[54:55], v[192:193] op_sel_hi:[1,0]
	v_pk_mul_f32 v[52:53], v[52:53], v[192:193] op_sel_hi:[1,0]
	v_pk_mul_f32 v[50:51], v[50:51], v[192:193] op_sel_hi:[1,0]
	v_pk_mul_f32 v[48:49], v[48:49], v[192:193] op_sel_hi:[1,0]
	v_pk_mul_f32 v[46:47], v[46:47], v[192:193] op_sel_hi:[1,0]
	v_pk_mul_f32 v[44:45], v[44:45], v[192:193] op_sel_hi:[1,0]
	v_pk_mul_f32 v[42:43], v[42:43], v[192:193] op_sel_hi:[1,0]
	v_pk_mul_f32 v[40:41], v[40:41], v[192:193] op_sel_hi:[1,0]
	v_pk_mul_f32 v[38:39], v[38:39], v[192:193] op_sel_hi:[1,0]
	v_pk_mul_f32 v[36:37], v[36:37], v[192:193] op_sel_hi:[1,0]
	v_pk_mul_f32 v[34:35], v[34:35], v[192:193] op_sel_hi:[1,0]
	v_pk_mul_f32 v[32:33], v[32:33], v[192:193] op_sel_hi:[1,0]
	v_pk_mul_f32 v[30:31], v[30:31], v[192:193] op_sel_hi:[1,0]
	v_pk_mul_f32 v[28:29], v[28:29], v[192:193] op_sel_hi:[1,0]
	v_pk_mul_f32 v[26:27], v[26:27], v[192:193] op_sel_hi:[1,0]
	v_pk_mul_f32 v[24:25], v[24:25], v[192:193] op_sel_hi:[1,0]
	v_pk_mul_f32 v[22:23], v[22:23], v[192:193] op_sel_hi:[1,0]
	v_pk_mul_f32 v[20:21], v[20:21], v[192:193] op_sel_hi:[1,0]
	v_pk_mul_f32 v[18:19], v[18:19], v[192:193] op_sel_hi:[1,0]
	v_pk_mul_f32 v[16:17], v[16:17], v[192:193] op_sel_hi:[1,0]
	v_pk_mul_f32 v[14:15], v[14:15], v[192:193] op_sel_hi:[1,0]
	v_pk_mul_f32 v[12:13], v[12:13], v[192:193] op_sel_hi:[1,0]
	v_pk_mul_f32 v[10:11], v[10:11], v[192:193] op_sel_hi:[1,0]
	v_pk_mul_f32 v[8:9], v[8:9], v[192:193] op_sel_hi:[1,0]
	v_pk_mul_f32 v[6:7], v[6:7], v[192:193] op_sel_hi:[1,0]
	v_pk_mul_f32 v[4:5], v[4:5], v[192:193] op_sel_hi:[1,0]
	v_pk_mul_f32 v[2:3], v[2:3], v[192:193] op_sel_hi:[1,0]
	v_pk_mul_f32 v[0:1], v[0:1], v[192:193] op_sel_hi:[1,0]
	v_mul_f32_e32 v180, v180, v192
	v_add_f32_e32 v80, v80, v244
	v_add_f32_e32 v81, v81, v244
	v_add_f32_e32 v82, v82, v244
	v_add_f32_e32 v83, v83, v244
	v_add_f32_e32 v84, v84, v244
	v_add_f32_e32 v85, v85, v244
	v_add_f32_e32 v86, v86, v244
	v_add_f32_e32 v87, v87, v244
	v_add_f32_e32 v88, v88, v244
	v_add_f32_e32 v89, v89, v244
	v_add_f32_e32 v90, v90, v244
	v_add_f32_e32 v91, v91, v244
	v_add_f32_e32 v92, v92, v244
	v_add_f32_e32 v93, v93, v244
	v_add_f32_e32 v94, v94, v244
	v_add_f32_e32 v95, v95, v244
	v_add_f32_e32 v64, v64, v244
	v_add_f32_e32 v65, v65, v244
	v_add_f32_e32 v66, v66, v244
	v_add_f32_e32 v67, v67, v244
	v_add_f32_e32 v68, v68, v244
	v_add_f32_e32 v69, v69, v244
	v_add_f32_e32 v70, v70, v244
	v_add_f32_e32 v71, v71, v244
	v_add_f32_e32 v72, v72, v244
	v_add_f32_e32 v73, v73, v244
	v_add_f32_e32 v74, v74, v244
	v_add_f32_e32 v75, v75, v244
	v_add_f32_e32 v76, v76, v244
	v_add_f32_e32 v77, v77, v244
	v_add_f32_e32 v78, v78, v244
	v_add_f32_e32 v79, v79, v244
	v_sub_f32_e32 v226, 0, v193
	v_mov_b32_e32 v227, v226
	v_mov_b32_e32 v228, v226
	v_mov_b32_e32 v229, v226
	v_mov_b32_e32 v230, v226
	v_mov_b32_e32 v231, v226
	v_mov_b32_e32 v232, v226
	v_mov_b32_e32 v233, v226
	v_mov_b32_e32 v234, v226
	v_mov_b32_e32 v235, v226
	v_mov_b32_e32 v236, v226
	v_mov_b32_e32 v237, v226
	v_mov_b32_e32 v238, v226
	v_mov_b32_e32 v239, v226
	v_mov_b32_e32 v240, v226
	v_mov_b32_e32 v241, v226
; __device__ __forceinline__ unsigned pk2(float a, float b) { f32x2_t v = {a, b}; bf16x2v_t r = __builtin_convertvector(v, bf16x2v_t); return __builtin_bit_cast(unsigned, r); }
; __device__ __forceinline__ void attn_unit(LAS unsigned char* lds, const bf16_t* Qg, const bf16_t* Kg, const bf16_t* Vtg, bf16_t* Og, int bh, int qb, int tid_, int wave, int lane_) {
;     ...
;         float ps = 0.f; u32x4 p0, p1;
; #pragma unroll
;         for (int q = 0; q < 4; ++q) sn = MFMA32(fb[q], qf[4 + q], sn);
; #pragma unroll
;         for (int i = 0; i < 8; ++i) { sc[i] = __builtin_amdgcn_exp2f(sc[i] - mrun); ps += sc[i]; }
;         p0.x = pk2(sc[0], sc[1]); p0.y = pk2(sc[2], sc[3]); p0.z = pk2(sc[4], sc[5]); p0.w = pk2(sc[6], sc[7]);
;         __builtin_amdgcn_sched_barrier(0);
; #pragma unroll
;         for (int dt = 0; dt < 4; ++dt) fb[dt] = *(const LAS bf16x8*)(vb + vro[0] + dt * 4096);
;         __builtin_amdgcn_sched_barrier(0);
;         ATT_ISSUE_K(j3, s0);
;         __builtin_amdgcn_sched_barrier(0);
; #pragma unroll
;         for (int q = 0; q < 4; ++q) sn = MFMA32(fa[q], qf[8 + q], sn);
; #pragma unroll
;         for (int i = 8; i < 12; ++i) { sc[i] = __builtin_amdgcn_exp2f(sc[i] - mrun); ps += sc[i]; }
;         p1.x = pk2(sc[8], sc[9]); p1.y = pk2(sc[10], sc[11]);
;         __builtin_amdgcn_sched_barrier(0);
;         ATT_ISSUE_V(j2, s2);
;         __builtin_amdgcn_sched_barrier(0);
; #pragma unroll
;         for (int dt = 0; dt < 4; ++dt) fa[dt] = *(const LAS bf16x8*)(vb + vro[1] + dt * 4096);
;         { const bf16x8 pf0 = __builtin_bit_cast(bf16x8, p0);
;           o[0] = MFMA32(fb[0], pf0, o[0]); o[1] = MFMA32(fb[1], pf0, o[1]); o[2] = MFMA32(fb[2], pf0, o[2]); o[3] = MFMA32(fb[3], pf0, o[3]); }
; #pragma unroll
;         for (int i = 12; i < 16; ++i) { sc[i] = __builtin_amdgcn_exp2f(sc[i] - mrun); ps += sc[i]; }
;         p1.z = pk2(sc[12], sc[13]); p1.w = pk2(sc[14], sc[15]);
;         lrun += ps;
;         __builtin_amdgcn_sched_barrier(0);
;         { const bf16x8 pf1 = __builtin_bit_cast(bf16x8, p1);
;           o[0] = MFMA32(fa[0], pf1, o[0]); o[1] = MFMA32(fa[1], pf1, o[1]); o[2] = MFMA32(fa[2], pf1, o[2]); o[3] = MFMA32(fa[3], pf1, o[3]); }
;         asm volatile("s_waitcnt vmcnt(5) lgkmcnt(0)" ::: "memory"); __builtin_amdgcn_s_barrier(); asm volatile("" ::: "memory");
;         sc = sn;
;         { const int t = s0; s0 = s1; s1 = s2; s2 = t; }
;     }
.Lattb_u2_492:
	v_mfma_f32_32x32x16_bf16 v[64:79], v[164:167], v[112:115], v[64:79]
	v_exp_f32_e32 v192, v80
	v_exp_f32_e32 v193, v81
	v_exp_f32_e32 v194, v82
	s_waitcnt lgkmcnt(0)
	v_mfma_f32_32x32x16_bf16 v[64:79], v[172:175], v[116:119], v[64:79]
	v_exp_f32_e32 v207, v83
	v_exp_f32_e32 v208, v84
	v_exp_f32_e32 v209, v85
	v_exp_f32_e32 v210, v86
	v_mfma_f32_32x32x16_bf16 v[64:79], v[168:171], v[120:123], v[64:79]
	s_add_i32 s0, s57, 3
	v_exp_f32_e32 v211, v87
	s_cmp_lt_i32 s0, s45
	s_cselect_b32 s0, s0, s44
	s_add_i32 s1, s57, 2
	s_cmp_lt_i32 s57, s52
	s_cselect_b32 s48, s1, s44
	v_cvt_pk_bf16_f32 v246, v192, v193
	v_cvt_pk_bf16_f32 v247, v194, v207
	v_cvt_pk_bf16_f32 v248, v208, v209
	v_cvt_pk_bf16_f32 v249, v210, v211
	ds_read_b128 v[214:217], v225 offset:32768
	ds_read_b128 v[164:167], v225 offset:36864
	ds_read_b128 v[168:171], v225 offset:40960
	ds_read_b128 v[172:175], v225 offset:45056
	v_add_f32_e32 v192, v193, v192
	v_add_f32_e32 v192, v194, v192
	v_add_f32_e32 v192, v207, v192
	v_add_f32_e32 v192, v208, v192
	v_add_f32_e32 v192, v209, v192
	v_add_f32_e32 v192, v210, v192
	v_add_f32_e32 v194, v211, v192
	s_mul_hi_u32 s1, s0, 0x6000
	s_mulk_i32 s0, 0x6000
	s_add_u32 s0, s92, s0
	s_mul_i32 s12, s58, 0x6000
	s_addc_u32 s1, s93, s1
	s_add_i32 s12, s71, s12
	s_mov_b32 m0, s12
	s_waitcnt lgkmcnt(5)
	v_mfma_f32_32x32x16_bf16 v[64:79], v[160:163], v[124:127], v[64:79]
	global_load_lds_dwordx4 v182, s[0:1]
	s_add_i32 m0, s12, 0x400
	s_nop 0
	global_load_lds_dwordx4 v184, s[0:1]
	s_add_i32 m0, s12, 0x800
	s_nop 0
	global_load_lds_dwordx4 v186, s[0:1]
	v_mfma_f32_32x32x16_bf16 v[64:79], v[148:151], v[128:131], v[64:79]
	v_exp_f32_e32 v220, v88
	v_exp_f32_e32 v221, v89
	v_exp_f32_e32 v222, v90
	v_mfma_f32_32x32x16_bf16 v[64:79], v[156:159], v[132:135], v[64:79]
	v_exp_f32_e32 v223, v91
	v_add_f32_e32 v148, v220, v194
	v_add_f32_e32 v148, v221, v148
	v_add_f32_e32 v148, v222, v148
	v_add_f32_e32 v156, v223, v148
	v_cvt_pk_bf16_f32 v250, v220, v221
	v_cvt_pk_bf16_f32 v251, v222, v223
	v_mfma_f32_32x32x16_bf16 v[64:79], v[152:155], v[136:139], v[64:79]
	v_exp_f32_e32 v220, v92
	v_exp_f32_e32 v221, v93
	v_exp_f32_e32 v222, v94
	v_exp_f32_e32 v223, v95
	s_waitcnt lgkmcnt(0)
	v_mfma_f32_32x32x16_bf16 v[80:95], v[144:147], v[140:143], v[64:79]
	s_lshl_b64 s[0:1], s[48:49], 7
	s_add_u32 s0, s94, s0
	s_addc_u32 s1, s95, s1
	s_lshl_b32 s12, s53, 14
	s_add_i32 s12, s12, 0
	s_add_i32 s12, s12, s68
	s_add_i32 m0, s12, 0x12000
	s_nop 0
	global_load_lds_dwordx4 v176, s[0:1]
	s_add_i32 m0, s12, 0x12400
	s_nop 0
	global_load_lds_dwordx4 v188, s[0:1]
	v_mfma_f32_32x32x16_bf16 v[48:63], v[214:217], v[246:249], v[48:63]
	ds_read_b128 v[214:217], v245 offset:32768
	ds_read_b128 v[144:147], v245 offset:36864
	ds_read_b128 v[148:151], v245 offset:40960
	ds_read_b128 v[152:155], v245 offset:45056
	v_mfma_f32_32x32x16_bf16 v[32:47], v[164:167], v[246:249], v[32:47]
	v_add_f32_e32 v213, v220, v156
	v_add_f32_e32 v213, v221, v213
	v_add_f32_e32 v213, v222, v213
	v_add_f32_e32 v213, v223, v213
	v_add_f32_e32 v180, v180, v213
	v_mfma_f32_32x32x16_bf16 v[16:31], v[168:171], v[246:249], v[16:31]
	v_cvt_pk_bf16_f32 v252, v220, v221
	v_cvt_pk_bf16_f32 v253, v222, v223
	v_mfma_f32_32x32x16_bf16 v[0:15], v[172:175], v[246:249], v[0:15]
	s_waitcnt lgkmcnt(0)
	v_mfma_f32_32x32x16_bf16 v[48:63], v[214:217], v[250:253], v[48:63]
	s_waitcnt vmcnt(5) lgkmcnt(0)
	s_barrier
	s_add_i32 s57, s57, 1
	s_add_i32 s56, s56, 64
	s_cmp_eq_u32 s45, s57
	v_mfma_f32_32x32x16_bf16 v[32:47], v[144:147], v[250:253], v[32:47]
	v_mfma_f32_32x32x16_bf16 v[16:31], v[148:151], v[250:253], v[16:31]
	v_mfma_f32_32x32x16_bf16 v[0:15], v[152:155], v[250:253], v[0:15]
	s_cbranch_scc1 .LBB0_495
	s_mov_b32 s0, s55
	s_mov_b32 s55, s53
	s_mov_b32 s53, s58
	s_add_i32 s1, s54, s56
	s_cmp_lt_i32 s1, 0
	s_mov_b32 s58, s0
	s_cbranch_scc0 .LBB0_488
	s_branch .LBB0_489
